# merge split into two passes with a grid barrier between: gate GEMM ops evenly distributed over all blocks using the gemm_in-style pipelined k-loop, then branch GEMM ops from the stashed gates
# speedup vs baseline: 1.0444x; 1.0444x over previous
; #define LAS __attribute__((address_space(3)))
; DI unsigned xb_add(unsigned* p, unsigned v) { return __hip_atomic_fetch_add(p, v, __ATOMIC_RELAXED, __HIP_MEMORY_SCOPE_AGENT); }
; DI unsigned xb_xcc_id() { return (unsigned)__builtin_amdgcn_s_getreg((3 << 11) | 20) & 0xFu; }
; DI XcdBarrier xcd_barrier_post(unsigned* bar) {
;     XcdBarrier b; b.bar = bar; b.x = xb_xcc_id(); b.nloc = 0u; b.nx = 0u;
;     if (threadIdx.x == 0) (void)xb_add(&bar[XB_XCNT(b.x)], 1u);
;     return b;
; __global__ void __launch_bounds__(256, 2) mega(Params p) {
;     __shared__ __attribute__((aligned(16))) char smem[65536];
;     LAS char* lds = (LAS char*)smem;
;     cg::grid_group grid = cg::this_grid();
;     XcdBarrier xb = xcd_barrier_post((unsigned*)(p.ws + OFF_BAR));
_Z4mega6Params:
	s_load_dwordx16 s[84:99], s[0:1], 0x80
	s_load_dwordx4 s[20:23], s[0:1], 0xc0
	s_load_dword s25, s[0:1], 0xd0
	s_add_u32 s14, s0, 0xc8
	s_addc_u32 s15, s1, 0
	s_getreg_b32 s4, hwreg(HW_REG_XCC_ID, 0, 4)
	s_waitcnt lgkmcnt(0)
	s_mov_b32 s101, 0
	s_add_u32 s10, s98, 0x1f120c00
	v_and_b32_e32 v151, 0x3ff, v0
	s_addc_u32 s11, s99, 0
	s_and_b32 s28, s4, 15
	v_cmp_eq_u32_e64 s[16:17], 0, v151
	s_and_saveexec_b64 s[4:5], s[16:17]
	s_cbranch_execz .LBB0_3
	s_mov_b64 s[6:7], exec
	v_mbcnt_lo_u32_b32 v1, s6, 0
	v_mbcnt_hi_u32_b32 v1, s7, v1
	v_cmp_eq_u32_e32 vcc, 0, v1
	s_and_b64 s[8:9], exec, vcc
	s_mov_b64 exec, s[8:9]
	s_cbranch_execz .LBB0_3
	s_lshl_b32 s8, s28, 8
	s_bcnt1_i32_b64 s6, s[6:7]
	v_mov_b32_e32 v1, s8
	v_mov_b32_e32 v2, s6
	global_atomic_add v1, v2, s[10:11] offset:1024

; __global__ void __launch_bounds__(256, 2) mega(Params p) {
;     ...
;     for (int ph = p.phase_lo; ph <= p.phase_hi; ++ph) {
.LBB0_7:
	s_add_i32 s0, s20, 1
	s_cmp_eq_u32 s101, 1
	s_cselect_b32 s0, s20, s0
	s_mov_b64 s[38:39], 0
	s_waitcnt vmcnt(63) expcnt(7) lgkmcnt(15)

; #define LAS __attribute__((address_space(3)))
; DI int otid() { int t = threadIdx.x; asm volatile("" : "+v"(t)); return t; }
; DI void phase_wo(const Params& p, int l, LAS char* lds) {
;     const int tidx = otid();
;     const bf16_t* m = (const bf16_t*)(p.ws + OFF_ZM);
;     const bf16_t* W = (const bf16_t*)(p.ws + OFF_W) + (size_t)l * W_LAYER + W_O;
;     bf16_t* o = (bf16_t*)(p.ws + OFF_H);
;     const int lane = tidx & 63, w = tidx >> 6, wm = w >> 1, wn = w & 1, fr = lane & 15, fq = lane >> 4;
;     auto op_of = [&](int i) { const int mt = i >> 3, nt = i & 7; return GOp{m + (size_t)mt * 128 * 1024, W + (size_t)nt * 128 * 1024, 1024, 1024, 1024, 2 * (mt + nt)}; };
;     bool inflight = false;
; __global__ void __launch_bounds__(256, 2) mega(Params p) {
;     ...
;             const int l = (ph - 1) / 7, s = (ph - 1) % 7;
;             switch (s) {
;                 case 0: for (int r = 0; r < REP_IN; ++r) phase_gemm_in(p, l, lds); break;
;                 case 1: for (int r = 0; r < REP_MIX; ++r) phase_mixers(p, l, lds); break;
;                 case 2: for (int r = 0; r < REP_QKV; ++r) phase_qkv(p, l, lds); break;
;                 case 3: for (int r = 0; r < REP_ATTN; ++r) phase_attn(p, l, lds); break;
;                 case 4: for (int r = 0; r < REP_MERGE; ++r) phase_merge(p, l, lds); break;
;                 case 5: for (int r = 0; r < REP_WO; ++r) phase_wo(p, l, lds); break;
.LBB0_9:
	s_cmp_lg_u32 s20, 0
	s_mov_b64 s[38:39], -1
	s_cbranch_scc0 .LBB0_404
	s_add_i32 s0, s20, -1
	s_mul_hi_i32 s1, s0, 0x92492493
	s_add_i32 s1, s1, s0
	s_lshr_b32 s4, s1, 31
	s_ashr_i32 s1, s1, 2
	s_add_i32 s1, s1, s4
	v_writelane_b32 v228, s1, 30
	s_mul_i32 s1, s1, 7
	s_sub_i32 s0, s0, s1
	s_mov_b64 s[46:47], 0
	s_cmp_lt_i32 s0, 3
	s_mov_b64 s[80:81], 0
	s_cbranch_scc1 .LBB0_16
	s_cmp_gt_i32 s0, 3
	s_cbranch_scc0 .LBB0_133
	s_cmp_gt_i32 s0, 4
	s_cbranch_scc0 .LBB0_134
	v_readlane_b32 s74, v231, 2
	s_mov_b32 s83, s0
	s_cmp_eq_u32 s0, 5
	s_mov_b64 s[80:81], -1
	v_readlane_b32 s75, v231, 3
	v_readlane_b32 s73, v229, 39
	s_movk_i32 s76, 0x1000
	s_movk_i32 s77, 0x300
	s_mov_b32 s78, 0x850000
	s_movk_i32 s79, 0x200
	s_cbranch_scc0 .LBB0_229
	v_readlane_b32 s0, v229, 23
	v_readlane_b32 s1, v229, 24
	v_mov_b32_e32 v2, v151
	s_and_b64 vcc, exec, s[0:1]
	s_cbranch_vccz .LBB0_228
	v_readlane_b32 s1, v228, 30
	s_mul_hi_i32 s0, s1, 0x13a0000
	s_mul_i32 s1, s1, 0x13a0000
	s_add_u32 s1, s98, s1
	s_addc_u32 s4, s99, s0
	s_add_u32 s0, s1, 0x11a0000
	s_addc_u32 s1, s4, 0
	v_and_b32_e32 v5, 48, v2
	v_lshrrev_b32_e32 v4, 4, v2
	v_lshlrev_b32_e32 v9, 3, v2
	s_movk_i32 s4, 0x70
	v_and_b32_e32 v3, 15, v2
	v_and_b32_e32 v10, 64, v2
	v_xor_b32_e32 v4, v4, v2
	v_lshlrev_b32_e32 v7, 7, v2
	v_bitop3_b32 v11, v9, v2, 48 bitop3:0x78
	v_bitop3_b32 v76, v9, s4, v5 bitop3:0x48
	v_ashrrev_i32_e32 v5, 1, v2
	s_movk_i32 s4, 0xffc0
	v_and_b32_e32 v6, 0xfffffc00, v7
	v_lshlrev_b32_e32 v4, 3, v4
	v_and_or_b32 v77, v5, s4, v3
	v_bitop3_b32 v80, v11, 64, v168 bitop3:0x6c
	v_lshlrev_b32_e32 v10, 1, v10
	v_mov_b32_e32 v11, v149
	v_and_b32_e32 v3, 16, v2
	v_lshlrev_b32_e32 v1, 4, v2
	v_and_or_b32 v148, v4, 56, v6
	v_lshl_add_u64 v[10:11], s[26:27], 0, v[10:11]
	v_lshlrev_b32_e32 v12, 1, v3
	v_mov_b32_e32 v13, v149
	v_lshrrev_b32_e32 v2, 1, v2
	v_and_b32_e32 v1, 0xfffffc00, v1
	v_add_u32_e32 v4, 0x8000, v148
	v_add_u32_e32 v6, 0x10000, v148
	v_add_u32_e32 v8, 0x18000, v148
	v_lshlrev_b32_e32 v78, 7, v77
	v_and_b32_e32 v79, 0x2780, v7
	v_mov_b32_e32 v5, v149
	v_mov_b32_e32 v7, v149
	v_mov_b32_e32 v9, v149
	v_lshl_add_u64 v[10:11], v[10:11], 0, v[12:13]
	v_and_b32_e32 v2, 16, v2
	v_mov_b32_e32 v3, v149
	v_lshl_add_u64 v[66:67], v[10:11], 0, v[2:3]
	s_mov_b64 s[40:41], 0
	v_lshlrev_b64 v[68:69], 1, v[148:149]
	v_add_u32_e32 v81, 0x4000, v1
	v_lshlrev_b64 v[70:71], 1, v[4:5]
	v_add_u32_e32 v82, 0x1000, v1
	v_add_u32_e32 v83, 0x5000, v1
	v_lshlrev_b64 v[72:73], 1, v[6:7]
	v_add_u32_e32 v84, 0x2000, v1
	v_add_u32_e32 v85, 0x6000, v1
	v_lshlrev_b64 v[74:75], 1, v[8:9]
	v_add_u32_e32 v86, 0x3000, v1
	v_add_u32_e32 v87, 0x7000, v1
	v_add_u32_e32 v88, 0x8000, v1
	v_add_u32_e32 v89, 0xc000, v1
	v_add_u32_e32 v90, 0x9000, v1
	v_add_u32_e32 v91, 0xd000, v1
	v_add_u32_e32 v92, 0xa000, v1
	v_add_u32_e32 v93, 0xe000, v1
	v_add_u32_e32 v94, 0xb000, v1
	v_add_u32_e32 v95, 0xf000, v1
	v_add_u32_e32 v96, v78, v76
	v_add_u32_e32 v97, v79, v76
	v_add_u32_e32 v98, v78, v80
	v_add_u32_e32 v99, v79, v80
	s_mov_b32 s23, s73
	s_mov_b32 s33, s73
	v_readfirstlane_b32 s100, v1
	s_branch .LBB0_22

; #define LAS __attribute__((address_space(3)))
; DI void gload_lds16(const void* g, LAS char* l) { __builtin_amdgcn_global_load_lds((const unsigned*)g, (LAS unsigned*)l, 16, 0, 0); }
; DI int vblock() { const int G = gridDim.x; return (G & 7) ? (int)blockIdx.x : (int)((blockIdx.x & 7) * (G >> 3) + (blockIdx.x >> 3)); }
; DI void gemm_issue(const GOp& g, int kt, LAS char* stage, int w, int lane) {
;     const int nk = g.K >> 6;
;     const int kk = ((kt + g.krot) & (nk - 1)) * 64;
;     LAS char* base = stage + w * 1024;
; #pragma unroll
;     for (int j = 0; j < 4; ++j) {
;         const int o = (j * 4 + w) * 1024 + lane * 16, row = o >> 7, cs = (o >> 4) & 7, c = cs ^ ((row >> 1) & 7);
;         gload_lds16(g.A + kk + (unsigned)(row * g.lda + c * 8), base + j * 4096);
;         gload_lds16(g.Bt + kk + (unsigned)(row * g.ldb + c * 8), base + 16384 + j * 4096);
;     }
; }
; DI void phase_wo(const Params& p, int l, LAS char* lds) {
;     ...
;     for (int i = vblock(); i < 257 * 8; i += gridDim.x) {
;         const int mt = i >> 3, nt = i & 7;
;         const bool has_next = i + (int)gridDim.x < 257 * 8;
;         const GOp g = op_of(i), gn = op_of(has_next ? i + (int)gridDim.x : i);
;         f32x4 acc[4][4]; zero_acc(acc);
;         gemm_core<true>(acc, g, lds, tidx, inflight, has_next, gn, true);
.LBB0_22:
	s_ashr_i32 s38, s33, 3
	s_ashr_i32 s39, s38, 31
	s_and_b32 s6, s33, 7
	s_lshl_b64 s[4:5], s[38:39], 18
	s_add_u32 s39, s18, s4
	s_addc_u32 s44, s19, s5
	s_lshl_b32 s4, s6, 18
	s_add_u32 s45, s0, s4
	s_addc_u32 s48, s1, 0
	s_add_i32 s4, s38, s6
	s_lshl_b32 s9, s4, 7
	s_mov_b32 s34, s9
	s_and_b64 vcc, exec, s[40:41]
	s_add_i32 s42, s33, s22
	s_cmpk_lt_i32 s42, 0x808
	s_cselect_b64 s[40:41], -1, 0
	s_cbranch_vccnz .Lwo_have
	s_and_b32 s4, s34, 0x3c0
	s_lshl_b32 s6, s4, 1
	s_add_u32 s4, s39, s6
	s_addc_u32 s5, s44, 0
	s_add_u32 s6, s45, s6
	s_addc_u32 s7, s48, 0
	s_add_i32 s34, s34, 64
	s_add_u32 m0, s100, 0x0
	s_nop 0
	global_load_lds_dwordx4 v68, s[4:5]
	s_add_u32 m0, s100, 0x4000
	s_nop 0
	global_load_lds_dwordx4 v68, s[6:7]
	s_add_u32 m0, s100, 0x1000
	s_nop 0
	global_load_lds_dwordx4 v70, s[4:5]
	s_add_u32 m0, s100, 0x5000
	s_nop 0
	global_load_lds_dwordx4 v70, s[6:7]
	s_add_u32 m0, s100, 0x2000
	s_nop 0
	global_load_lds_dwordx4 v72, s[4:5]
	s_add_u32 m0, s100, 0x6000
	s_nop 0
	global_load_lds_dwordx4 v72, s[6:7]
	s_add_u32 m0, s100, 0x3000
	s_nop 0
	global_load_lds_dwordx4 v74, s[4:5]
	s_add_u32 m0, s100, 0x7000
	s_nop 0
	global_load_lds_dwordx4 v74, s[6:7]
	s_and_b32 s4, s34, 0x3c0
	s_lshl_b32 s6, s4, 1
	s_add_u32 s4, s39, s6
	s_addc_u32 s5, s44, 0
	s_add_u32 s6, s45, s6
	s_addc_u32 s7, s48, 0
	s_add_i32 s34, s34, 64
	s_add_u32 m0, s100, 0x8000
	s_nop 0
	global_load_lds_dwordx4 v68, s[4:5]
	s_add_u32 m0, s100, 0xc000
	s_nop 0
	global_load_lds_dwordx4 v68, s[6:7]
	s_add_u32 m0, s100, 0x9000
	s_nop 0
	global_load_lds_dwordx4 v70, s[4:5]
	s_add_u32 m0, s100, 0xd000
	s_nop 0
	global_load_lds_dwordx4 v70, s[6:7]
	s_add_u32 m0, s100, 0xa000
	s_nop 0
	global_load_lds_dwordx4 v72, s[4:5]
	s_add_u32 m0, s100, 0xe000
	s_nop 0
	global_load_lds_dwordx4 v72, s[6:7]
	s_add_u32 m0, s100, 0xb000
	s_nop 0
	global_load_lds_dwordx4 v74, s[4:5]
	s_add_u32 m0, s100, 0xf000
	s_nop 0
	global_load_lds_dwordx4 v74, s[6:7]
	s_waitcnt vmcnt(8)
	s_branch .Lwo_k0

; template <bool WIDE = false>
; DI void gemm_core(f32x4 (&acc)[4][4], const GOp& g, LAS char* lds, const int tidx, const bool have_first, const bool has_next, const GOp& gn, const bool fw16 = false) {
;     ...
;     for (int kt = 0; kt < nk; ++kt) {
;         if (kt == 0 && have_first && fw16) {
;             asm volatile("s_waitcnt vmcnt(8) lgkmcnt(0)" ::: "memory");
;             __builtin_amdgcn_s_barrier();
;             asm volatile("" ::: "memory");
;         } else {
;             asm volatile("s_waitcnt vmcnt(0)" ::: "memory");
;             __syncthreads();
;         }
;         if (kt + 1 < nk) {
;             LAS char* base = lds + ((kt + 1) & 1) * 32768 + w * 1024;
;             const int kn = ((kt + 1 + g.krot) & (nk - 1)) * 64;
;             const bf16_t* Ak = g.A + kn; const bf16_t* Bk = g.Bt + kn;
; #pragma unroll
;             for (int j = 0; j < 4; ++j) { gload_lds16(Ak + oa[j], base + j * 4096); gload_lds16(Bk + ob[j], base + 16384 + j * 4096); }
;         } else if (has_next) gemm_issue(gn, 0, lds, w, lane);
;         LAS char* st = lds + (kt & 1) * 32768;
;         if constexpr (WIDE) {
;         bf16x8 af[2][4], bfr[2][4];
; #pragma unroll
;         for (int ks = 0; ks < 2; ++ks) {
; #pragma unroll
;             for (int i = 0; i < 4; ++i) af[ks][i] = *(LAS bf16x8*)(st + aoff + i * 2048 + (sw ^ (ks * 64)));
; #pragma unroll
;             for (int i = 0; i < 4; ++i) bfr[ks][i] = *(LAS bf16x8*)(st + boff + i * 2048 + (sw ^ (ks * 64)));
;         }
;         __builtin_amdgcn_sched_barrier(0);
;         __builtin_amdgcn_s_setprio(1);
; #pragma unroll
;         for (int ks = 0; ks < 2; ++ks)
; #pragma unroll
;             for (int mi = 0; mi < 4; ++mi)
; #pragma unroll
;                 for (int ni = 0; ni < 4; ++ni) acc[mi][ni] = __builtin_amdgcn_mfma_f32_16x16x32_bf16(bfr[ks][ni], af[ks][mi], acc[mi][ni], 0, 0, 0);
;         __builtin_amdgcn_s_setprio(0);
;         } else {
; #pragma unroll
;         for (int ks = 0; ks < 2; ++ks) {
;             bf16x8 af[4], bfr[4];
; #pragma unroll
;             for (int i = 0; i < 4; ++i) af[i] = *(LAS bf16x8*)(st + aoff + i * 2048 + (sw ^ (ks * 64)));
; #pragma unroll
;             for (int i = 0; i < 4; ++i) bfr[i] = *(LAS bf16x8*)(st + boff + i * 2048 + (sw ^ (ks * 64)));
;             __builtin_amdgcn_s_setprio(1);
; #pragma unroll
;             for (int mi = 0; mi < 4; ++mi)
; #pragma unroll
.Lwo_k0:
	s_barrier
	ds_read_b128 v[100:103], v96 offset:0
	ds_read_b128 v[104:107], v96 offset:2048
	ds_read_b128 v[108:111], v96 offset:4096
	ds_read_b128 v[112:115], v96 offset:6144
	ds_read_b128 v[116:119], v97 offset:16384
	ds_read_b128 v[120:123], v97 offset:18432
	ds_read_b128 v[124:127], v97 offset:20480
	ds_read_b128 v[128:131], v97 offset:22528
	ds_read_b128 v[132:135], v98 offset:0
	ds_read_b128 v[136:139], v98 offset:2048
	ds_read_b128 v[140:143], v98 offset:4096
	ds_read_b128 v[144:147], v98 offset:6144
	ds_read_b128 v[152:155], v99 offset:16384
	ds_read_b128 v[156:159], v99 offset:18432
	ds_read_b128 v[178:181], v99 offset:20480
	ds_read_b128 v[182:185], v99 offset:22528
	s_waitcnt lgkmcnt(0)
	s_barrier
	s_and_b32 s4, s34, 0x3c0
	s_lshl_b32 s6, s4, 1
	s_add_u32 s4, s39, s6
	s_addc_u32 s5, s44, 0
	s_add_u32 s6, s45, s6
	s_addc_u32 s7, s48, 0
	s_add_i32 s34, s34, 64
	s_setprio 1
	s_add_u32 m0, s100, 0x0
	v_mfma_f32_16x16x32_bf16 v[62:65], v[116:119], v[100:103], 0
	global_load_lds_dwordx4 v68, s[4:5]
	v_mfma_f32_16x16x32_bf16 v[58:61], v[120:123], v[100:103], 0
	s_add_u32 m0, s100, 0x4000
	v_mfma_f32_16x16x32_bf16 v[54:57], v[124:127], v[100:103], 0
	global_load_lds_dwordx4 v68, s[6:7]
	v_mfma_f32_16x16x32_bf16 v[50:53], v[128:131], v[100:103], 0
	s_add_u32 m0, s100, 0x1000
	v_mfma_f32_16x16x32_bf16 v[46:49], v[116:119], v[104:107], 0
	global_load_lds_dwordx4 v70, s[4:5]
	v_mfma_f32_16x16x32_bf16 v[42:45], v[120:123], v[104:107], 0
	s_add_u32 m0, s100, 0x5000
	v_mfma_f32_16x16x32_bf16 v[38:41], v[124:127], v[104:107], 0
	global_load_lds_dwordx4 v70, s[6:7]
	v_mfma_f32_16x16x32_bf16 v[34:37], v[128:131], v[104:107], 0
	s_add_u32 m0, s100, 0x2000
	v_mfma_f32_16x16x32_bf16 v[30:33], v[116:119], v[108:111], 0
	global_load_lds_dwordx4 v72, s[4:5]
	v_mfma_f32_16x16x32_bf16 v[26:29], v[120:123], v[108:111], 0
	s_add_u32 m0, s100, 0x6000
	v_mfma_f32_16x16x32_bf16 v[22:25], v[124:127], v[108:111], 0
	global_load_lds_dwordx4 v72, s[6:7]
	v_mfma_f32_16x16x32_bf16 v[18:21], v[128:131], v[108:111], 0
	s_add_u32 m0, s100, 0x3000
	v_mfma_f32_16x16x32_bf16 v[14:17], v[116:119], v[112:115], 0
	global_load_lds_dwordx4 v74, s[4:5]
	v_mfma_f32_16x16x32_bf16 v[10:13], v[120:123], v[112:115], 0
	s_add_u32 m0, s100, 0x7000
	v_mfma_f32_16x16x32_bf16 v[6:9], v[124:127], v[112:115], 0
	global_load_lds_dwordx4 v74, s[6:7]
	v_mfma_f32_16x16x32_bf16 v[2:5], v[128:131], v[112:115], 0
	v_mfma_f32_16x16x32_bf16 v[62:65], v[152:155], v[132:135], v[62:65]
	v_mfma_f32_16x16x32_bf16 v[58:61], v[156:159], v[132:135], v[58:61]
	v_mfma_f32_16x16x32_bf16 v[54:57], v[178:181], v[132:135], v[54:57]
	v_mfma_f32_16x16x32_bf16 v[50:53], v[182:185], v[132:135], v[50:53]
	v_mfma_f32_16x16x32_bf16 v[46:49], v[152:155], v[136:139], v[46:49]
	v_mfma_f32_16x16x32_bf16 v[42:45], v[156:159], v[136:139], v[42:45]
	v_mfma_f32_16x16x32_bf16 v[38:41], v[178:181], v[136:139], v[38:41]
	v_mfma_f32_16x16x32_bf16 v[34:37], v[182:185], v[136:139], v[34:37]
	v_mfma_f32_16x16x32_bf16 v[30:33], v[152:155], v[140:143], v[30:33]
	v_mfma_f32_16x16x32_bf16 v[26:29], v[156:159], v[140:143], v[26:29]
	v_mfma_f32_16x16x32_bf16 v[22:25], v[178:181], v[140:143], v[22:25]
	v_mfma_f32_16x16x32_bf16 v[18:21], v[182:185], v[140:143], v[18:21]
	v_mfma_f32_16x16x32_bf16 v[14:17], v[152:155], v[144:147], v[14:17]
	v_mfma_f32_16x16x32_bf16 v[10:13], v[156:159], v[144:147], v[10:13]
	v_mfma_f32_16x16x32_bf16 v[6:9], v[178:181], v[144:147], v[6:9]
	v_mfma_f32_16x16x32_bf16 v[2:5], v[182:185], v[144:147], v[2:5]
	s_setprio 0
	s_waitcnt vmcnt(8)
	s_barrier
	ds_read_b128 v[100:103], v96 offset:32768
	ds_read_b128 v[104:107], v96 offset:34816
	ds_read_b128 v[108:111], v96 offset:36864
	ds_read_b128 v[112:115], v96 offset:38912
	ds_read_b128 v[116:119], v97 offset:49152
	ds_read_b128 v[120:123], v97 offset:51200
	ds_read_b128 v[124:127], v97 offset:53248
	ds_read_b128 v[128:131], v97 offset:55296
	ds_read_b128 v[132:135], v98 offset:32768
	ds_read_b128 v[136:139], v98 offset:34816
	ds_read_b128 v[140:143], v98 offset:36864
	ds_read_b128 v[144:147], v98 offset:38912
	ds_read_b128 v[152:155], v99 offset:49152
	ds_read_b128 v[156:159], v99 offset:51200
	ds_read_b128 v[178:181], v99 offset:53248
	ds_read_b128 v[182:185], v99 offset:55296
	s_waitcnt lgkmcnt(0)
	s_barrier
; template <bool WIDE = false>
; DI void gemm_core(f32x4 (&acc)[4][4], const GOp& g, LAS char* lds, const int tidx, const bool have_first, const bool has_next, const GOp& gn, const bool fw16 = false) {
;     ...
;     for (int kt = 0; kt < nk; ++kt) {
;         if (kt == 0 && have_first && fw16) {
;             asm volatile("s_waitcnt vmcnt(8) lgkmcnt(0)" ::: "memory");
;             __builtin_amdgcn_s_barrier();
;             asm volatile("" ::: "memory");
;         } else {
;             asm volatile("s_waitcnt vmcnt(0)" ::: "memory");
;             __syncthreads();
;         }
;         if (kt + 1 < nk) {
;             LAS char* base = lds + ((kt + 1) & 1) * 32768 + w * 1024;
;             const int kn = ((kt + 1 + g.krot) & (nk - 1)) * 64;
;             const bf16_t* Ak = g.A + kn; const bf16_t* Bk = g.Bt + kn;
; #pragma unroll
;             for (int j = 0; j < 4; ++j) { gload_lds16(Ak + oa[j], base + j * 4096); gload_lds16(Bk + ob[j], base + 16384 + j * 4096); }
;         } else if (has_next) gemm_issue(gn, 0, lds, w, lane);
;         LAS char* st = lds + (kt & 1) * 32768;
;         if constexpr (WIDE) {
;         bf16x8 af[2][4], bfr[2][4];
; #pragma unroll
;         for (int ks = 0; ks < 2; ++ks) {
; #pragma unroll
;             for (int i = 0; i < 4; ++i) af[ks][i] = *(LAS bf16x8*)(st + aoff + i * 2048 + (sw ^ (ks * 64)));
; #pragma unroll
;             for (int i = 0; i < 4; ++i) bfr[ks][i] = *(LAS bf16x8*)(st + boff + i * 2048 + (sw ^ (ks * 64)));
;         }
;         __builtin_amdgcn_sched_barrier(0);
;         __builtin_amdgcn_s_setprio(1);
; #pragma unroll
;         for (int ks = 0; ks < 2; ++ks)
; #pragma unroll
;             for (int mi = 0; mi < 4; ++mi)
; #pragma unroll
;                 for (int ni = 0; ni < 4; ++ni) acc[mi][ni] = __builtin_amdgcn_mfma_f32_16x16x32_bf16(bfr[ks][ni], af[ks][mi], acc[mi][ni], 0, 0, 0);
;         __builtin_amdgcn_s_setprio(0);
;         } else {
; #pragma unroll
;         for (int ks = 0; ks < 2; ++ks) {
;             bf16x8 af[4], bfr[4];
; #pragma unroll
;             for (int i = 0; i < 4; ++i) af[i] = *(LAS bf16x8*)(st + aoff + i * 2048 + (sw ^ (ks * 64)));
; #pragma unroll
;             for (int i = 0; i < 4; ++i) bfr[i] = *(LAS bf16x8*)(st + boff + i * 2048 + (sw ^ (ks * 64)));
;             __builtin_amdgcn_s_setprio(1);
; #pragma unroll
;             for (int mi = 0; mi < 4; ++mi)
; #pragma unroll
	s_and_b32 s4, s34, 0x3c0
	s_lshl_b32 s6, s4, 1
	s_add_u32 s4, s39, s6
	s_addc_u32 s5, s44, 0
	s_add_u32 s6, s45, s6
	s_addc_u32 s7, s48, 0
	s_add_i32 s34, s34, 64
	s_setprio 1
	s_add_u32 m0, s100, 0x8000
	v_mfma_f32_16x16x32_bf16 v[62:65], v[116:119], v[100:103], v[62:65]
	global_load_lds_dwordx4 v68, s[4:5]
	v_mfma_f32_16x16x32_bf16 v[58:61], v[120:123], v[100:103], v[58:61]
	s_add_u32 m0, s100, 0xc000
	v_mfma_f32_16x16x32_bf16 v[54:57], v[124:127], v[100:103], v[54:57]
	global_load_lds_dwordx4 v68, s[6:7]
	v_mfma_f32_16x16x32_bf16 v[50:53], v[128:131], v[100:103], v[50:53]
	s_add_u32 m0, s100, 0x9000
	v_mfma_f32_16x16x32_bf16 v[46:49], v[116:119], v[104:107], v[46:49]
	global_load_lds_dwordx4 v70, s[4:5]
	v_mfma_f32_16x16x32_bf16 v[42:45], v[120:123], v[104:107], v[42:45]
	s_add_u32 m0, s100, 0xd000
	v_mfma_f32_16x16x32_bf16 v[38:41], v[124:127], v[104:107], v[38:41]
	global_load_lds_dwordx4 v70, s[6:7]
	v_mfma_f32_16x16x32_bf16 v[34:37], v[128:131], v[104:107], v[34:37]
	s_add_u32 m0, s100, 0xa000
	v_mfma_f32_16x16x32_bf16 v[30:33], v[116:119], v[108:111], v[30:33]
	global_load_lds_dwordx4 v72, s[4:5]
	v_mfma_f32_16x16x32_bf16 v[26:29], v[120:123], v[108:111], v[26:29]
	s_add_u32 m0, s100, 0xe000
	v_mfma_f32_16x16x32_bf16 v[22:25], v[124:127], v[108:111], v[22:25]
	global_load_lds_dwordx4 v72, s[6:7]
	v_mfma_f32_16x16x32_bf16 v[18:21], v[128:131], v[108:111], v[18:21]
	s_add_u32 m0, s100, 0xb000
	v_mfma_f32_16x16x32_bf16 v[14:17], v[116:119], v[112:115], v[14:17]
	global_load_lds_dwordx4 v74, s[4:5]
	v_mfma_f32_16x16x32_bf16 v[10:13], v[120:123], v[112:115], v[10:13]
	s_add_u32 m0, s100, 0xf000
	v_mfma_f32_16x16x32_bf16 v[6:9], v[124:127], v[112:115], v[6:9]
	global_load_lds_dwordx4 v74, s[6:7]
	v_mfma_f32_16x16x32_bf16 v[2:5], v[128:131], v[112:115], v[2:5]
	v_mfma_f32_16x16x32_bf16 v[62:65], v[152:155], v[132:135], v[62:65]
	v_mfma_f32_16x16x32_bf16 v[58:61], v[156:159], v[132:135], v[58:61]
	v_mfma_f32_16x16x32_bf16 v[54:57], v[178:181], v[132:135], v[54:57]
	v_mfma_f32_16x16x32_bf16 v[50:53], v[182:185], v[132:135], v[50:53]
	v_mfma_f32_16x16x32_bf16 v[46:49], v[152:155], v[136:139], v[46:49]
	v_mfma_f32_16x16x32_bf16 v[42:45], v[156:159], v[136:139], v[42:45]
	v_mfma_f32_16x16x32_bf16 v[38:41], v[178:181], v[136:139], v[38:41]
	v_mfma_f32_16x16x32_bf16 v[34:37], v[182:185], v[136:139], v[34:37]
	v_mfma_f32_16x16x32_bf16 v[30:33], v[152:155], v[140:143], v[30:33]
	v_mfma_f32_16x16x32_bf16 v[26:29], v[156:159], v[140:143], v[26:29]
	v_mfma_f32_16x16x32_bf16 v[22:25], v[178:181], v[140:143], v[22:25]
	v_mfma_f32_16x16x32_bf16 v[18:21], v[182:185], v[140:143], v[18:21]
	v_mfma_f32_16x16x32_bf16 v[14:17], v[152:155], v[144:147], v[14:17]
	v_mfma_f32_16x16x32_bf16 v[10:13], v[156:159], v[144:147], v[10:13]
	v_mfma_f32_16x16x32_bf16 v[6:9], v[178:181], v[144:147], v[6:9]
	v_mfma_f32_16x16x32_bf16 v[2:5], v[182:185], v[144:147], v[2:5]
	s_setprio 0
	s_mov_b32 s43, 6
.Lwo_loop:
	s_waitcnt vmcnt(8)
	s_barrier
	ds_read_b128 v[100:103], v96 offset:0
	ds_read_b128 v[104:107], v96 offset:2048
	ds_read_b128 v[108:111], v96 offset:4096
	ds_read_b128 v[112:115], v96 offset:6144
	ds_read_b128 v[116:119], v97 offset:16384
	ds_read_b128 v[120:123], v97 offset:18432
	ds_read_b128 v[124:127], v97 offset:20480
	ds_read_b128 v[128:131], v97 offset:22528
	ds_read_b128 v[132:135], v98 offset:0
	ds_read_b128 v[136:139], v98 offset:2048
	ds_read_b128 v[140:143], v98 offset:4096
	ds_read_b128 v[144:147], v98 offset:6144
	ds_read_b128 v[152:155], v99 offset:16384
	ds_read_b128 v[156:159], v99 offset:18432
	ds_read_b128 v[178:181], v99 offset:20480
	ds_read_b128 v[182:185], v99 offset:22528
	s_waitcnt lgkmcnt(0)
	s_barrier
	s_and_b32 s4, s34, 0x3c0
	s_lshl_b32 s6, s4, 1
	s_add_u32 s4, s39, s6
	s_addc_u32 s5, s44, 0
	s_add_u32 s6, s45, s6
	s_addc_u32 s7, s48, 0
	s_add_i32 s34, s34, 64
	s_setprio 1
	s_add_u32 m0, s100, 0x0
	v_mfma_f32_16x16x32_bf16 v[62:65], v[116:119], v[100:103], v[62:65]
	global_load_lds_dwordx4 v68, s[4:5]
	v_mfma_f32_16x16x32_bf16 v[58:61], v[120:123], v[100:103], v[58:61]
	s_add_u32 m0, s100, 0x4000
	v_mfma_f32_16x16x32_bf16 v[54:57], v[124:127], v[100:103], v[54:57]
	global_load_lds_dwordx4 v68, s[6:7]
	v_mfma_f32_16x16x32_bf16 v[50:53], v[128:131], v[100:103], v[50:53]
	s_add_u32 m0, s100, 0x1000
	v_mfma_f32_16x16x32_bf16 v[46:49], v[116:119], v[104:107], v[46:49]
	global_load_lds_dwordx4 v70, s[4:5]
	v_mfma_f32_16x16x32_bf16 v[42:45], v[120:123], v[104:107], v[42:45]
	s_add_u32 m0, s100, 0x5000
	v_mfma_f32_16x16x32_bf16 v[38:41], v[124:127], v[104:107], v[38:41]
	global_load_lds_dwordx4 v70, s[6:7]
	v_mfma_f32_16x16x32_bf16 v[34:37], v[128:131], v[104:107], v[34:37]
	s_add_u32 m0, s100, 0x2000
	v_mfma_f32_16x16x32_bf16 v[30:33], v[116:119], v[108:111], v[30:33]
	global_load_lds_dwordx4 v72, s[4:5]
	v_mfma_f32_16x16x32_bf16 v[26:29], v[120:123], v[108:111], v[26:29]
	s_add_u32 m0, s100, 0x6000
	v_mfma_f32_16x16x32_bf16 v[22:25], v[124:127], v[108:111], v[22:25]
	global_load_lds_dwordx4 v72, s[6:7]
	v_mfma_f32_16x16x32_bf16 v[18:21], v[128:131], v[108:111], v[18:21]
	s_add_u32 m0, s100, 0x3000
	v_mfma_f32_16x16x32_bf16 v[14:17], v[116:119], v[112:115], v[14:17]
	global_load_lds_dwordx4 v74, s[4:5]
	v_mfma_f32_16x16x32_bf16 v[10:13], v[120:123], v[112:115], v[10:13]
	s_add_u32 m0, s100, 0x7000
	v_mfma_f32_16x16x32_bf16 v[6:9], v[124:127], v[112:115], v[6:9]
	global_load_lds_dwordx4 v74, s[6:7]
	v_mfma_f32_16x16x32_bf16 v[2:5], v[128:131], v[112:115], v[2:5]
	v_mfma_f32_16x16x32_bf16 v[62:65], v[152:155], v[132:135], v[62:65]
	v_mfma_f32_16x16x32_bf16 v[58:61], v[156:159], v[132:135], v[58:61]
	v_mfma_f32_16x16x32_bf16 v[54:57], v[178:181], v[132:135], v[54:57]
	v_mfma_f32_16x16x32_bf16 v[50:53], v[182:185], v[132:135], v[50:53]
	v_mfma_f32_16x16x32_bf16 v[46:49], v[152:155], v[136:139], v[46:49]
	v_mfma_f32_16x16x32_bf16 v[42:45], v[156:159], v[136:139], v[42:45]
	v_mfma_f32_16x16x32_bf16 v[38:41], v[178:181], v[136:139], v[38:41]
	v_mfma_f32_16x16x32_bf16 v[34:37], v[182:185], v[136:139], v[34:37]
	v_mfma_f32_16x16x32_bf16 v[30:33], v[152:155], v[140:143], v[30:33]
	v_mfma_f32_16x16x32_bf16 v[26:29], v[156:159], v[140:143], v[26:29]
	v_mfma_f32_16x16x32_bf16 v[22:25], v[178:181], v[140:143], v[22:25]
	v_mfma_f32_16x16x32_bf16 v[18:21], v[182:185], v[140:143], v[18:21]
	v_mfma_f32_16x16x32_bf16 v[14:17], v[152:155], v[144:147], v[14:17]
	v_mfma_f32_16x16x32_bf16 v[10:13], v[156:159], v[144:147], v[10:13]
	v_mfma_f32_16x16x32_bf16 v[6:9], v[178:181], v[144:147], v[6:9]
	v_mfma_f32_16x16x32_bf16 v[2:5], v[182:185], v[144:147], v[2:5]
	s_setprio 0
	s_waitcnt vmcnt(8)
	s_barrier
; template <bool WIDE = false>
; DI void gemm_core(f32x4 (&acc)[4][4], const GOp& g, LAS char* lds, const int tidx, const bool have_first, const bool has_next, const GOp& gn, const bool fw16 = false) {
;     ...
;     for (int kt = 0; kt < nk; ++kt) {
;         if (kt == 0 && have_first && fw16) {
;             asm volatile("s_waitcnt vmcnt(8) lgkmcnt(0)" ::: "memory");
;             __builtin_amdgcn_s_barrier();
;             asm volatile("" ::: "memory");
;         } else {
;             asm volatile("s_waitcnt vmcnt(0)" ::: "memory");
;             __syncthreads();
;         }
;         if (kt + 1 < nk) {
;             LAS char* base = lds + ((kt + 1) & 1) * 32768 + w * 1024;
;             const int kn = ((kt + 1 + g.krot) & (nk - 1)) * 64;
;             const bf16_t* Ak = g.A + kn; const bf16_t* Bk = g.Bt + kn;
; #pragma unroll
;             for (int j = 0; j < 4; ++j) { gload_lds16(Ak + oa[j], base + j * 4096); gload_lds16(Bk + ob[j], base + 16384 + j * 4096); }
;         } else if (has_next) gemm_issue(gn, 0, lds, w, lane);
;         LAS char* st = lds + (kt & 1) * 32768;
;         if constexpr (WIDE) {
;         bf16x8 af[2][4], bfr[2][4];
; #pragma unroll
;         for (int ks = 0; ks < 2; ++ks) {
; #pragma unroll
;             for (int i = 0; i < 4; ++i) af[ks][i] = *(LAS bf16x8*)(st + aoff + i * 2048 + (sw ^ (ks * 64)));
; #pragma unroll
;             for (int i = 0; i < 4; ++i) bfr[ks][i] = *(LAS bf16x8*)(st + boff + i * 2048 + (sw ^ (ks * 64)));
;         }
;         __builtin_amdgcn_sched_barrier(0);
;         __builtin_amdgcn_s_setprio(1);
; #pragma unroll
;         for (int ks = 0; ks < 2; ++ks)
; #pragma unroll
;             for (int mi = 0; mi < 4; ++mi)
; #pragma unroll
;                 for (int ni = 0; ni < 4; ++ni) acc[mi][ni] = __builtin_amdgcn_mfma_f32_16x16x32_bf16(bfr[ks][ni], af[ks][mi], acc[mi][ni], 0, 0, 0);
;         __builtin_amdgcn_s_setprio(0);
;         } else {
; #pragma unroll
;         for (int ks = 0; ks < 2; ++ks) {
;             bf16x8 af[4], bfr[4];
; #pragma unroll
;             for (int i = 0; i < 4; ++i) af[i] = *(LAS bf16x8*)(st + aoff + i * 2048 + (sw ^ (ks * 64)));
; #pragma unroll
;             for (int i = 0; i < 4; ++i) bfr[i] = *(LAS bf16x8*)(st + boff + i * 2048 + (sw ^ (ks * 64)));
;             __builtin_amdgcn_s_setprio(1);
; #pragma unroll
;             for (int mi = 0; mi < 4; ++mi)
; #pragma unroll
	ds_read_b128 v[100:103], v96 offset:32768
	ds_read_b128 v[104:107], v96 offset:34816
	ds_read_b128 v[108:111], v96 offset:36864
	ds_read_b128 v[112:115], v96 offset:38912
	ds_read_b128 v[116:119], v97 offset:49152
	ds_read_b128 v[120:123], v97 offset:51200
	ds_read_b128 v[124:127], v97 offset:53248
	ds_read_b128 v[128:131], v97 offset:55296
	ds_read_b128 v[132:135], v98 offset:32768
	ds_read_b128 v[136:139], v98 offset:34816
	ds_read_b128 v[140:143], v98 offset:36864
	ds_read_b128 v[144:147], v98 offset:38912
	ds_read_b128 v[152:155], v99 offset:49152
	ds_read_b128 v[156:159], v99 offset:51200
	ds_read_b128 v[178:181], v99 offset:53248
	ds_read_b128 v[182:185], v99 offset:55296
	s_waitcnt lgkmcnt(0)
	s_barrier
	s_and_b32 s4, s34, 0x3c0
	s_lshl_b32 s6, s4, 1
	s_add_u32 s4, s39, s6
	s_addc_u32 s5, s44, 0
	s_add_u32 s6, s45, s6
	s_addc_u32 s7, s48, 0
	s_add_i32 s34, s34, 64
	s_setprio 1
	s_add_u32 m0, s100, 0x8000
	v_mfma_f32_16x16x32_bf16 v[62:65], v[116:119], v[100:103], v[62:65]
	global_load_lds_dwordx4 v68, s[4:5]
	v_mfma_f32_16x16x32_bf16 v[58:61], v[120:123], v[100:103], v[58:61]
	s_add_u32 m0, s100, 0xc000
	v_mfma_f32_16x16x32_bf16 v[54:57], v[124:127], v[100:103], v[54:57]
	global_load_lds_dwordx4 v68, s[6:7]
	v_mfma_f32_16x16x32_bf16 v[50:53], v[128:131], v[100:103], v[50:53]
	s_add_u32 m0, s100, 0x9000
	v_mfma_f32_16x16x32_bf16 v[46:49], v[116:119], v[104:107], v[46:49]
	global_load_lds_dwordx4 v70, s[4:5]
	v_mfma_f32_16x16x32_bf16 v[42:45], v[120:123], v[104:107], v[42:45]
	s_add_u32 m0, s100, 0xd000
	v_mfma_f32_16x16x32_bf16 v[38:41], v[124:127], v[104:107], v[38:41]
	global_load_lds_dwordx4 v70, s[6:7]
	v_mfma_f32_16x16x32_bf16 v[34:37], v[128:131], v[104:107], v[34:37]
	s_add_u32 m0, s100, 0xa000
	v_mfma_f32_16x16x32_bf16 v[30:33], v[116:119], v[108:111], v[30:33]
	global_load_lds_dwordx4 v72, s[4:5]
	v_mfma_f32_16x16x32_bf16 v[26:29], v[120:123], v[108:111], v[26:29]
	s_add_u32 m0, s100, 0xe000
	v_mfma_f32_16x16x32_bf16 v[22:25], v[124:127], v[108:111], v[22:25]
	global_load_lds_dwordx4 v72, s[6:7]
	v_mfma_f32_16x16x32_bf16 v[18:21], v[128:131], v[108:111], v[18:21]
	s_add_u32 m0, s100, 0xb000
	v_mfma_f32_16x16x32_bf16 v[14:17], v[116:119], v[112:115], v[14:17]
	global_load_lds_dwordx4 v74, s[4:5]
	v_mfma_f32_16x16x32_bf16 v[10:13], v[120:123], v[112:115], v[10:13]
	s_add_u32 m0, s100, 0xf000
	v_mfma_f32_16x16x32_bf16 v[6:9], v[124:127], v[112:115], v[6:9]
	global_load_lds_dwordx4 v74, s[6:7]
	v_mfma_f32_16x16x32_bf16 v[2:5], v[128:131], v[112:115], v[2:5]
	v_mfma_f32_16x16x32_bf16 v[62:65], v[152:155], v[132:135], v[62:65]
	v_mfma_f32_16x16x32_bf16 v[58:61], v[156:159], v[132:135], v[58:61]
	v_mfma_f32_16x16x32_bf16 v[54:57], v[178:181], v[132:135], v[54:57]
	v_mfma_f32_16x16x32_bf16 v[50:53], v[182:185], v[132:135], v[50:53]
	v_mfma_f32_16x16x32_bf16 v[46:49], v[152:155], v[136:139], v[46:49]
	v_mfma_f32_16x16x32_bf16 v[42:45], v[156:159], v[136:139], v[42:45]
	v_mfma_f32_16x16x32_bf16 v[38:41], v[178:181], v[136:139], v[38:41]
	v_mfma_f32_16x16x32_bf16 v[34:37], v[182:185], v[136:139], v[34:37]
	v_mfma_f32_16x16x32_bf16 v[30:33], v[152:155], v[140:143], v[30:33]
	v_mfma_f32_16x16x32_bf16 v[26:29], v[156:159], v[140:143], v[26:29]
	v_mfma_f32_16x16x32_bf16 v[22:25], v[178:181], v[140:143], v[22:25]
	v_mfma_f32_16x16x32_bf16 v[18:21], v[182:185], v[140:143], v[18:21]
	v_mfma_f32_16x16x32_bf16 v[14:17], v[152:155], v[144:147], v[14:17]
	v_mfma_f32_16x16x32_bf16 v[10:13], v[156:159], v[144:147], v[10:13]
	v_mfma_f32_16x16x32_bf16 v[6:9], v[178:181], v[144:147], v[6:9]
	v_mfma_f32_16x16x32_bf16 v[2:5], v[182:185], v[144:147], v[2:5]
	s_setprio 0
	s_add_i32 s43, s43, -1
	s_cmp_lg_u32 s43, 0
	s_cbranch_scc1 .Lwo_loop
	s_waitcnt vmcnt(8)
	s_barrier
; #define LAS __attribute__((address_space(3)))
; DI void gload_lds16(const void* g, LAS char* l) { __builtin_amdgcn_global_load_lds((const unsigned*)g, (LAS unsigned*)l, 16, 0, 0); }
; template <bool WIDE = false>
; DI void gemm_core(f32x4 (&acc)[4][4], const GOp& g, LAS char* lds, const int tidx, const bool have_first, const bool has_next, const GOp& gn, const bool fw16 = false) {
;     ...
;         if (kt + 1 < nk) {
;             LAS char* base = lds + ((kt + 1) & 1) * 32768 + w * 1024;
;             const int kn = ((kt + 1 + g.krot) & (nk - 1)) * 64;
;             const bf16_t* Ak = g.A + kn; const bf16_t* Bk = g.Bt + kn;
; #pragma unroll
;             for (int j = 0; j < 4; ++j) { gload_lds16(Ak + oa[j], base + j * 4096); gload_lds16(Bk + ob[j], base + 16384 + j * 4096); }
;         } else if (has_next) gemm_issue(gn, 0, lds, w, lane);
;     ...
;         for (int ks = 0; ks < 2; ++ks)
; #pragma unroll
;             for (int mi = 0; mi < 4; ++mi)
; #pragma unroll
;                 for (int ni = 0; ni < 4; ++ni) acc[mi][ni] = __builtin_amdgcn_mfma_f32_16x16x32_bf16(bfr[ks][ni], af[ks][mi], acc[mi][ni], 0, 0, 0);
	ds_read_b128 v[100:103], v96 offset:0
	ds_read_b128 v[104:107], v96 offset:2048
	ds_read_b128 v[108:111], v96 offset:4096
	ds_read_b128 v[112:115], v96 offset:6144
	ds_read_b128 v[116:119], v97 offset:16384
	ds_read_b128 v[120:123], v97 offset:18432
	ds_read_b128 v[124:127], v97 offset:20480
	ds_read_b128 v[128:131], v97 offset:22528
	ds_read_b128 v[132:135], v98 offset:0
	ds_read_b128 v[136:139], v98 offset:2048
	ds_read_b128 v[140:143], v98 offset:4096
	ds_read_b128 v[144:147], v98 offset:6144
	ds_read_b128 v[152:155], v99 offset:16384
	ds_read_b128 v[156:159], v99 offset:18432
	ds_read_b128 v[178:181], v99 offset:20480
	ds_read_b128 v[182:185], v99 offset:22528
	s_waitcnt lgkmcnt(0)
	s_barrier
	s_and_b64 vcc, exec, s[40:41]
	s_cbranch_vccz .Lwok14_ni
	s_ashr_i32 s8, s42, 3
	s_and_b32 s9, s42, 7
	s_add_i32 s4, s8, s9
	s_lshl_b32 s4, s4, 7
	s_and_b32 s4, s4, 0x3c0
	s_lshl_b32 s6, s4, 1
	s_lshl_b32 s4, s8, 18
	s_add_u32 s4, s4, s6
	s_add_u32 s4, s18, s4
	s_addc_u32 s5, s19, 0
	s_lshl_b32 s7, s9, 18
	s_add_u32 s6, s7, s6
	s_add_u32 s6, s0, s6
	s_addc_u32 s7, s1, 0
	s_setprio 1
	s_add_u32 m0, s100, 0x0
	v_mfma_f32_16x16x32_bf16 v[62:65], v[116:119], v[100:103], v[62:65]
	global_load_lds_dwordx4 v68, s[4:5]
	v_mfma_f32_16x16x32_bf16 v[58:61], v[120:123], v[100:103], v[58:61]
	s_add_u32 m0, s100, 0x4000
	v_mfma_f32_16x16x32_bf16 v[54:57], v[124:127], v[100:103], v[54:57]
	global_load_lds_dwordx4 v68, s[6:7]
	v_mfma_f32_16x16x32_bf16 v[50:53], v[128:131], v[100:103], v[50:53]
	s_add_u32 m0, s100, 0x1000
	v_mfma_f32_16x16x32_bf16 v[46:49], v[116:119], v[104:107], v[46:49]
	global_load_lds_dwordx4 v70, s[4:5]
	v_mfma_f32_16x16x32_bf16 v[42:45], v[120:123], v[104:107], v[42:45]
	s_add_u32 m0, s100, 0x5000
	v_mfma_f32_16x16x32_bf16 v[38:41], v[124:127], v[104:107], v[38:41]
	global_load_lds_dwordx4 v70, s[6:7]
	v_mfma_f32_16x16x32_bf16 v[34:37], v[128:131], v[104:107], v[34:37]
	s_add_u32 m0, s100, 0x2000
	v_mfma_f32_16x16x32_bf16 v[30:33], v[116:119], v[108:111], v[30:33]
	global_load_lds_dwordx4 v72, s[4:5]
	v_mfma_f32_16x16x32_bf16 v[26:29], v[120:123], v[108:111], v[26:29]
	s_add_u32 m0, s100, 0x6000
	v_mfma_f32_16x16x32_bf16 v[22:25], v[124:127], v[108:111], v[22:25]
	global_load_lds_dwordx4 v72, s[6:7]
	v_mfma_f32_16x16x32_bf16 v[18:21], v[128:131], v[108:111], v[18:21]
	s_add_u32 m0, s100, 0x3000
	v_mfma_f32_16x16x32_bf16 v[14:17], v[116:119], v[112:115], v[14:17]
	global_load_lds_dwordx4 v74, s[4:5]
	v_mfma_f32_16x16x32_bf16 v[10:13], v[120:123], v[112:115], v[10:13]
	s_add_u32 m0, s100, 0x7000
	v_mfma_f32_16x16x32_bf16 v[6:9], v[124:127], v[112:115], v[6:9]
	global_load_lds_dwordx4 v74, s[6:7]
	v_mfma_f32_16x16x32_bf16 v[2:5], v[128:131], v[112:115], v[2:5]
	v_mfma_f32_16x16x32_bf16 v[62:65], v[152:155], v[132:135], v[62:65]
	v_mfma_f32_16x16x32_bf16 v[58:61], v[156:159], v[132:135], v[58:61]
	v_mfma_f32_16x16x32_bf16 v[54:57], v[178:181], v[132:135], v[54:57]
	v_mfma_f32_16x16x32_bf16 v[50:53], v[182:185], v[132:135], v[50:53]
	v_mfma_f32_16x16x32_bf16 v[46:49], v[152:155], v[136:139], v[46:49]
	v_mfma_f32_16x16x32_bf16 v[42:45], v[156:159], v[136:139], v[42:45]
	v_mfma_f32_16x16x32_bf16 v[38:41], v[178:181], v[136:139], v[38:41]
	v_mfma_f32_16x16x32_bf16 v[34:37], v[182:185], v[136:139], v[34:37]
	v_mfma_f32_16x16x32_bf16 v[30:33], v[152:155], v[140:143], v[30:33]
	v_mfma_f32_16x16x32_bf16 v[26:29], v[156:159], v[140:143], v[26:29]
	v_mfma_f32_16x16x32_bf16 v[22:25], v[178:181], v[140:143], v[22:25]
	v_mfma_f32_16x16x32_bf16 v[18:21], v[182:185], v[140:143], v[18:21]
	v_mfma_f32_16x16x32_bf16 v[14:17], v[152:155], v[144:147], v[14:17]
	v_mfma_f32_16x16x32_bf16 v[10:13], v[156:159], v[144:147], v[10:13]
	v_mfma_f32_16x16x32_bf16 v[6:9], v[178:181], v[144:147], v[6:9]
	v_mfma_f32_16x16x32_bf16 v[2:5], v[182:185], v[144:147], v[2:5]
	s_setprio 0
	s_branch .Lwok14_dn

; #define LAS __attribute__((address_space(3)))
; DI void gload_lds16(const void* g, LAS char* l) { __builtin_amdgcn_global_load_lds((const unsigned*)g, (LAS unsigned*)l, 16, 0, 0); }
; template <bool WIDE = false>
; DI void gemm_core(f32x4 (&acc)[4][4], const GOp& g, LAS char* lds, const int tidx, const bool have_first, const bool has_next, const GOp& gn, const bool fw16 = false) {
;     ...
;         if (kt + 1 < nk) {
;             LAS char* base = lds + ((kt + 1) & 1) * 32768 + w * 1024;
;             const int kn = ((kt + 1 + g.krot) & (nk - 1)) * 64;
;             const bf16_t* Ak = g.A + kn; const bf16_t* Bk = g.Bt + kn;
; #pragma unroll
;             for (int j = 0; j < 4; ++j) { gload_lds16(Ak + oa[j], base + j * 4096); gload_lds16(Bk + ob[j], base + 16384 + j * 4096); }
;         } else if (has_next) gemm_issue(gn, 0, lds, w, lane);
;     ...
;         for (int ks = 0; ks < 2; ++ks)
; #pragma unroll
;             for (int mi = 0; mi < 4; ++mi)
; #pragma unroll
;                 for (int ni = 0; ni < 4; ++ni) acc[mi][ni] = __builtin_amdgcn_mfma_f32_16x16x32_bf16(bfr[ks][ni], af[ks][mi], acc[mi][ni], 0, 0, 0);
.Lwok15_wd:
	s_barrier
	ds_read_b128 v[100:103], v96 offset:32768
	ds_read_b128 v[104:107], v96 offset:34816
	ds_read_b128 v[108:111], v96 offset:36864
	ds_read_b128 v[112:115], v96 offset:38912
	ds_read_b128 v[116:119], v97 offset:49152
	ds_read_b128 v[120:123], v97 offset:51200
	ds_read_b128 v[124:127], v97 offset:53248
	ds_read_b128 v[128:131], v97 offset:55296
	ds_read_b128 v[132:135], v98 offset:32768
	ds_read_b128 v[136:139], v98 offset:34816
	ds_read_b128 v[140:143], v98 offset:36864
	ds_read_b128 v[144:147], v98 offset:38912
	ds_read_b128 v[152:155], v99 offset:49152
	ds_read_b128 v[156:159], v99 offset:51200
	ds_read_b128 v[178:181], v99 offset:53248
	ds_read_b128 v[182:185], v99 offset:55296
	s_waitcnt lgkmcnt(0)
	s_barrier
	s_and_b64 vcc, exec, s[40:41]
	s_cbranch_vccz .Lwok15_ni
	s_ashr_i32 s8, s42, 3
	s_and_b32 s9, s42, 7
	s_add_i32 s4, s8, s9
	s_lshl_b32 s4, s4, 7
	s_add_i32 s4, s4, 64
	s_and_b32 s4, s4, 0x3c0
	s_lshl_b32 s6, s4, 1
	s_lshl_b32 s4, s8, 18
	s_add_u32 s4, s4, s6
	s_add_u32 s4, s18, s4
	s_addc_u32 s5, s19, 0
	s_lshl_b32 s7, s9, 18
	s_add_u32 s6, s7, s6
	s_add_u32 s6, s0, s6
	s_addc_u32 s7, s1, 0
	s_setprio 1
	s_add_u32 m0, s100, 0x8000
	v_mfma_f32_16x16x32_bf16 v[62:65], v[116:119], v[100:103], v[62:65]
	global_load_lds_dwordx4 v68, s[4:5]
	v_mfma_f32_16x16x32_bf16 v[58:61], v[120:123], v[100:103], v[58:61]
	s_add_u32 m0, s100, 0xc000
	v_mfma_f32_16x16x32_bf16 v[54:57], v[124:127], v[100:103], v[54:57]
	global_load_lds_dwordx4 v68, s[6:7]
	v_mfma_f32_16x16x32_bf16 v[50:53], v[128:131], v[100:103], v[50:53]
	s_add_u32 m0, s100, 0x9000
	v_mfma_f32_16x16x32_bf16 v[46:49], v[116:119], v[104:107], v[46:49]
	global_load_lds_dwordx4 v70, s[4:5]
	v_mfma_f32_16x16x32_bf16 v[42:45], v[120:123], v[104:107], v[42:45]
	s_add_u32 m0, s100, 0xd000
	v_mfma_f32_16x16x32_bf16 v[38:41], v[124:127], v[104:107], v[38:41]
	global_load_lds_dwordx4 v70, s[6:7]
	v_mfma_f32_16x16x32_bf16 v[34:37], v[128:131], v[104:107], v[34:37]
	s_add_u32 m0, s100, 0xa000
	v_mfma_f32_16x16x32_bf16 v[30:33], v[116:119], v[108:111], v[30:33]
	global_load_lds_dwordx4 v72, s[4:5]
	v_mfma_f32_16x16x32_bf16 v[26:29], v[120:123], v[108:111], v[26:29]
	s_add_u32 m0, s100, 0xe000
	v_mfma_f32_16x16x32_bf16 v[22:25], v[124:127], v[108:111], v[22:25]
	global_load_lds_dwordx4 v72, s[6:7]
	v_mfma_f32_16x16x32_bf16 v[18:21], v[128:131], v[108:111], v[18:21]
	s_add_u32 m0, s100, 0xb000
	v_mfma_f32_16x16x32_bf16 v[14:17], v[116:119], v[112:115], v[14:17]
	global_load_lds_dwordx4 v74, s[4:5]
	v_mfma_f32_16x16x32_bf16 v[10:13], v[120:123], v[112:115], v[10:13]
	s_add_u32 m0, s100, 0xf000
	v_mfma_f32_16x16x32_bf16 v[6:9], v[124:127], v[112:115], v[6:9]
	global_load_lds_dwordx4 v74, s[6:7]
	v_mfma_f32_16x16x32_bf16 v[2:5], v[128:131], v[112:115], v[2:5]
	v_mfma_f32_16x16x32_bf16 v[62:65], v[152:155], v[132:135], v[62:65]
	v_mfma_f32_16x16x32_bf16 v[58:61], v[156:159], v[132:135], v[58:61]
	v_mfma_f32_16x16x32_bf16 v[54:57], v[178:181], v[132:135], v[54:57]
	v_mfma_f32_16x16x32_bf16 v[50:53], v[182:185], v[132:135], v[50:53]
	v_mfma_f32_16x16x32_bf16 v[46:49], v[152:155], v[136:139], v[46:49]
	v_mfma_f32_16x16x32_bf16 v[42:45], v[156:159], v[136:139], v[42:45]
	v_mfma_f32_16x16x32_bf16 v[38:41], v[178:181], v[136:139], v[38:41]
	v_mfma_f32_16x16x32_bf16 v[34:37], v[182:185], v[136:139], v[34:37]
	v_mfma_f32_16x16x32_bf16 v[30:33], v[152:155], v[140:143], v[30:33]
	v_mfma_f32_16x16x32_bf16 v[26:29], v[156:159], v[140:143], v[26:29]
	v_mfma_f32_16x16x32_bf16 v[22:25], v[178:181], v[140:143], v[22:25]
	v_mfma_f32_16x16x32_bf16 v[18:21], v[182:185], v[140:143], v[18:21]
	v_mfma_f32_16x16x32_bf16 v[14:17], v[152:155], v[144:147], v[14:17]
	v_mfma_f32_16x16x32_bf16 v[10:13], v[156:159], v[144:147], v[10:13]
	v_mfma_f32_16x16x32_bf16 v[6:9], v[178:181], v[144:147], v[6:9]
	v_mfma_f32_16x16x32_bf16 v[2:5], v[182:185], v[144:147], v[2:5]
	s_setprio 0
	s_branch .Lwok15_dn

; DI int vblock() { const int G = gridDim.x; return (G & 7) ? (int)blockIdx.x : (int)((blockIdx.x & 7) * (G >> 3) + (blockIdx.x >> 3)); }
; DI void phase_merge(const Params& p, int l, LAS char* lds) {
;     ...
;     const int G = gridDim.x, NT = 257 * 8, vb = vblock();
;     const int ntl = (vb < NT) ? (NT - vb + G - 1) / G : 0;
;     const int nops = 8 * ntl;
;     auto op_of = [&](int f) {
;         if (f < 4 * ntl) {
;             const int br = f / ntl, i = vb + (f - br * ntl) * G, mt = i >> 3, nt = i & 7;
;             return GOp{h + (size_t)mt * 128 * 1024, W + W_IN + (size_t)(3328 + br * 1024 + nt * 128) * 1024, 1024, 1024, 1024, 2 * (mt + nt)};
;         }
;         const int f2 = f - 4 * ntl, k = f2 >> 2, br = f2 & 3, i = vb + k * G, mt = i >> 3, nt = i & 7;
;         const int koff = (br == 0) ? 0 : (br == 1) ? 256 : (br == 2) ? 768 : 1024;
;         const int kk = (br == 1) ? 512 : 256;
;         const size_t woff = (br == 0) ? W_OP : (br == 1) ? W_OM : (br == 2) ? W_OC : W_OS;
;         return GOp{u + (size_t)mt * 128 * 1280 + koff, W + woff + (size_t)nt * 128 * kk, 1280, kk, kk, mt + nt};
;     };
;     f32x4 acc[4][4];
;     bool inflight = false;
;     unsigned sq[4][4], sqn[4][4];
; #pragma unroll
;     for (int mi = 0; mi < 4; ++mi)
; #pragma unroll
;         for (int ni = 0; ni < 4; ++ni) { sq[mi][ni] = 0x01010101u; sqn[mi][ni] = 0x01010101u; }
;     for (int f = 0; f < nops; ++f) {
;         const bool gate = f < 4 * ntl;
;         int br, i;
;         if (gate) { br = f / ntl; i = vb + (f - br * ntl) * G; } else { const int f2 = f - 4 * ntl; br = f2 & 3; i = vb + (f2 >> 2) * G; }
;         const int mt = i >> 3, nt = i & 7;
;         const bool has_next = f + 1 < nops;
;         const GOp g = op_of(f), gn = op_of(has_next ? f + 1 : f);
;         unsigned* st = stash + (size_t)(i * 4 + br) * 4096;
.LBB0_134:
	v_readlane_b32 s74, v231, 2
	s_mov_b32 s83, s0
	v_readlane_b32 s75, v231, 3
	v_readlane_b32 s73, v229, 39
	s_movk_i32 s76, 0x1000
	s_movk_i32 s77, 0x300
	s_mov_b32 s78, 0x850000
	s_movk_i32 s79, 0x200
	s_cmp_eq_u32 s101, 0
	s_cbranch_scc1 .Lgp_entry
	s_mov_b32 s101, 0
	s_and_b64 vcc, exec, s[38:39]
	s_cbranch_vccnz .LBB0_230
	s_branch .LBB0_278
.Lgp_entry:
	s_waitcnt vmcnt(0)
	v_mov_b32_e32 v2, v151
	v_lshlrev_b32_e32 v4, 4, v2
	v_and_b32_e32 v67, 0xfffffc00, v4
	v_lshrrev_b32_e32 v4, 4, v2
	v_xor_b32_e32 v4, v4, v2
	v_lshlrev_b32_e32 v7, 7, v2
	v_readlane_b32 s8, v228, 30
	v_and_b32_e32 v5, 48, v2
	v_and_b32_e32 v6, 0xfffffc00, v7
	v_lshlrev_b32_e32 v4, 3, v4
	v_lshlrev_b32_e32 v9, 3, v2
	s_movk_i32 s4, 0x70
	s_mul_i32 s0, s8, 0x13a0000
	v_and_b32_e32 v1, 64, v2
	v_and_b32_e32 v3, 15, v2
	v_and_or_b32 v148, v4, 56, v6
	v_bitop3_b32 v10, v9, v2, 48 bitop3:0x78
	v_bitop3_b32 v86, v9, s4, v5 bitop3:0x48
	v_ashrrev_i32_e32 v5, 1, v2
	s_movk_i32 s4, 0xffc0
	v_and_b32_e32 v66, 16, v2
	v_lshrrev_b32_e32 v2, 2, v2
	s_mul_hi_i32 s1, s8, 0x13a0000
	s_add_u32 s0, s98, s0
	v_add_u32_e32 v4, 0x8000, v148
	v_add_u32_e32 v6, 0x10000, v148
	v_add_u32_e32 v8, 0x18000, v148
	v_and_or_b32 v87, v5, s4, v3
	v_and_b32_e32 v89, 0x2780, v7
	v_mov_b32_e32 v5, v149
	v_mov_b32_e32 v7, v149
	v_mov_b32_e32 v9, v149
	v_and_b32_e32 v2, 8, v2
	s_addc_u32 s1, s99, s1
	v_lshlrev_b32_e32 v88, 7, v87
	v_bitop3_b32 v90, v10, 64, v168 bitop3:0x6c
	s_mov_b64 s[46:47], 0
	v_lshlrev_b32_e32 v68, 1, v2
	v_lshlrev_b64 v[70:71], 1, v[148:149]
	v_lshlrev_b64 v[72:73], 1, v[4:5]
	v_lshlrev_b64 v[74:75], 1, v[6:7]
	v_lshlrev_b64 v[76:77], 1, v[8:9]
	v_readlane_b32 s4, v229, 39
	v_readfirstlane_b32 s100, v67
	s_mov_b32 s56, s4
	v_lshlrev_b32_e32 v1, 2, v151
	v_and_b32_e32 v77, 64, v151
	v_lshrrev_b32_e32 v3, 2, v151
	v_and_b32_e32 v3, 12, v3
	v_or_b32_e32 v77, v77, v3
	v_lshlrev_b32_e32 v77, 2, v77
	v_readlane_b32 s60, v228, 19
	v_readlane_b32 s61, v228, 20
	v_readlane_b32 s62, v229, 53
	v_readlane_b32 s63, v229, 54
	s_lshl_b32 s5, s8, 14
	s_add_u32 s62, s62, s5
	s_addc_u32 s63, s63, 0
	s_cmpk_gt_u32 s56, 0x201f
	s_cbranch_scc1 .Lgp_done
.Lgp_tile:
	s_mov_b32 s55, s56
	s_mov_b32 s54, 0
	s_cmp_ge_u32 s55, 0x808
	s_cselect_b32 s5, 1, 0
	s_add_u32 s54, s54, s5
	s_mul_i32 s5, s5, 0x808
	s_sub_u32 s55, s55, s5
	s_cmp_ge_u32 s55, 0x808
	s_cselect_b32 s5, 1, 0
	s_add_u32 s54, s54, s5
	s_mul_i32 s5, s5, 0x808
	s_sub_u32 s55, s55, s5
	s_cmp_ge_u32 s55, 0x808
	s_cselect_b32 s5, 1, 0
	s_add_u32 s54, s54, s5
	s_mul_i32 s5, s5, 0x808
	s_sub_u32 s55, s55, s5
	s_lshr_b32 s48, s55, 3
	s_and_b32 s5, s55, 7
	s_lshl_b32 s6, s54, 3
	s_add_u32 s50, s5, s6
	s_add_u32 s50, s50, 26
	s_add_i32 s23, s56, s22
	s_cmpk_lt_u32 s23, 0x2020
	s_cselect_b64 s[42:43], -1, 0
	s_cbranch_scc0 .Lgp_nonext
	s_mov_b32 s52, s23
	s_mov_b32 s57, 0
	s_cmp_ge_u32 s52, 0x808
	s_cselect_b32 s5, 1, 0
	s_add_u32 s57, s57, s5
	s_mul_i32 s5, s5, 0x808
	s_sub_u32 s52, s52, s5
	s_cmp_ge_u32 s52, 0x808
	s_cselect_b32 s5, 1, 0
	s_add_u32 s57, s57, s5
	s_mul_i32 s5, s5, 0x808
	s_sub_u32 s52, s52, s5
	s_cmp_ge_u32 s52, 0x808
	s_cselect_b32 s5, 1, 0
	s_add_u32 s57, s57, s5
	s_mul_i32 s5, s5, 0x808
	s_sub_u32 s52, s52, s5
	s_lshr_b32 s38, s52, 3
	s_and_b32 s5, s52, 7
	s_lshl_b32 s6, s57, 3
	s_add_u32 s44, s5, s6
	s_add_u32 s44, s44, 26
; #define LAS __attribute__((address_space(3)))
; DI void gemm_issue(const GOp& g, int kt, LAS char* stage, int w, int lane) {
;     const int nk = g.K >> 6;
;     const int kk = ((kt + g.krot) & (nk - 1)) * 64;
;     LAS char* base = stage + w * 1024;
; #pragma unroll
;     for (int j = 0; j < 4; ++j) {
;         const int o = (j * 4 + w) * 1024 + lane * 16, row = o >> 7, cs = (o >> 4) & 7, c = cs ^ ((row >> 1) & 7);
;         gload_lds16(g.A + kk + (unsigned)(row * g.lda + c * 8), base + j * 4096);
;         gload_lds16(g.Bt + kk + (unsigned)(row * g.ldb + c * 8), base + 16384 + j * 4096);
;     }
; }
; template <bool WIDE = false>
; DI void gemm_core(f32x4 (&acc)[4][4], const GOp& g, LAS char* lds, const int tidx, const bool have_first, const bool has_next, const GOp& gn, const bool fw16 = false) {
;     const int tid = tidx, lane = tid & 63, w = tid >> 6, wm = w >> 1, wn = w & 1;
;     unsigned oa[4], ob[4];
; #pragma unroll
;     for (int j = 0; j < 4; ++j) {
;         const int o = (j * 4 + w) * 1024 + lane * 16, row = o >> 7, cs = (o >> 4) & 7, c = cs ^ ((row >> 1) & 7);
;         oa[j] = (unsigned)(row * g.lda + c * 8); ob[j] = (unsigned)(row * g.ldb + c * 8);
;     }
;     const int nk = g.K >> 6;
;     const int fr = lane & 15, fq = lane >> 4;
;     const int sw = (fq ^ (fr >> 1)) << 4;
;     const int aoff = (wm * 64 + fr) * 128, boff = 16384 + (wn * 64 + fr) * 128;
;     if (!have_first) gemm_issue(g, 0, lds, w, lane);
;     for (int kt = 0; kt < nk; ++kt) {
;         if (kt == 0 && have_first && fw16) {
;             asm volatile("s_waitcnt vmcnt(8) lgkmcnt(0)" ::: "memory");
;             __builtin_amdgcn_s_barrier();
;             asm volatile("" ::: "memory");
;         } else {
;             asm volatile("s_waitcnt vmcnt(0)" ::: "memory");
;             __syncthreads();
;         }
;         if (kt + 1 < nk) {
;             LAS char* base = lds + ((kt + 1) & 1) * 32768 + w * 1024;
;             const int kn = ((kt + 1 + g.krot) & (nk - 1)) * 64;
;             const bf16_t* Ak = g.A + kn; const bf16_t* Bk = g.Bt + kn;
; #pragma unroll
;             for (int j = 0; j < 4; ++j) { gload_lds16(Ak + oa[j], base + j * 4096); gload_lds16(Bk + ob[j], base + 16384 + j * 4096); }
;         } else if (has_next) gemm_issue(gn, 0, lds, w, lane);
; DI void phase_merge(const Params& p, int l, LAS char* lds) {
;     ...
;         if (gate) {
; #pragma unroll
.Lgp_nonext:
	s_lshl_b32 s5, s54, 12
	s_and_b32 s6, s55, 7
	s_lshl_b32 s6, s6, 9
	s_add_u32 s5, s5, s6
	s_add_u32 s6, s62, s5
	s_addc_u32 s7, s63, 0
	global_load_dword v66, v77, s[6:7] offset:0
	global_load_dword v68, v77, s[6:7] offset:4
	global_load_dword v69, v77, s[6:7] offset:8
	global_load_dword v93, v77, s[6:7] offset:12
	global_load_dword v146, v77, s[6:7] offset:64
	global_load_dword v147, v77, s[6:7] offset:68
	global_load_dword v148, v77, s[6:7] offset:72
	global_load_dword v160, v77, s[6:7] offset:76
	global_load_dword v161, v77, s[6:7] offset:128
	global_load_dword v182, v77, s[6:7] offset:132
	global_load_dword v183, v77, s[6:7] offset:136
	global_load_dword v184, v77, s[6:7] offset:140
	global_load_dword v185, v77, s[6:7] offset:192
	global_load_dword v71, v77, s[6:7] offset:196
	global_load_dword v73, v77, s[6:7] offset:200
	global_load_dword v75, v77, s[6:7] offset:204
	s_ashr_i32 s49, s48, 31
	s_lshl_b64 s[4:5], s[48:49], 18
	s_add_u32 s39, s26, s4
	s_addc_u32 s45, s27, s5
	s_ashr_i32 s51, s50, 31
	s_lshl_b64 s[4:5], s[50:51], 18
	s_add_u32 s49, s0, s4
	s_addc_u32 s51, s1, s5
	s_add_i32 s4, s50, s48
	s_lshl_b32 s48, s4, 7
	v_add_u32_e32 v226, v88, v86
	v_add_u32_e32 v227, v89, v86
	v_add_u32_e32 v91, v88, v90
	v_add_u32_e32 v92, v89, v90
	s_mov_b32 s34, s48
	s_and_b64 vcc, exec, s[46:47]
	s_cbranch_vccnz .Lgp_have
	s_and_b32 s4, s34, 0x3c0
	s_lshl_b32 s6, s4, 1
	s_add_u32 s4, s39, s6
	s_addc_u32 s5, s45, 0
	s_add_u32 s6, s49, s6
	s_addc_u32 s7, s51, 0
	s_add_i32 s34, s34, 64
	s_add_u32 m0, s100, 0x0
	s_nop 0
	global_load_lds_dwordx4 v70, s[4:5]
	s_add_u32 m0, s100, 0x4000
	s_nop 0
	global_load_lds_dwordx4 v70, s[6:7]
	s_add_u32 m0, s100, 0x1000
	s_nop 0
	global_load_lds_dwordx4 v72, s[4:5]
	s_add_u32 m0, s100, 0x5000
	s_nop 0
	global_load_lds_dwordx4 v72, s[6:7]
	s_add_u32 m0, s100, 0x2000
	s_nop 0
	global_load_lds_dwordx4 v74, s[4:5]
	s_add_u32 m0, s100, 0x6000
	s_nop 0
	global_load_lds_dwordx4 v74, s[6:7]
	s_add_u32 m0, s100, 0x3000
	s_nop 0
	global_load_lds_dwordx4 v76, s[4:5]
	s_add_u32 m0, s100, 0x7000
	s_nop 0
	global_load_lds_dwordx4 v76, s[6:7]
	s_and_b32 s4, s34, 0x3c0
	s_lshl_b32 s6, s4, 1
	s_add_u32 s4, s39, s6
	s_addc_u32 s5, s45, 0
	s_add_u32 s6, s49, s6
	s_addc_u32 s7, s51, 0
	s_add_i32 s34, s34, 64
	s_add_u32 m0, s100, 0x8000
	s_nop 0
	global_load_lds_dwordx4 v70, s[4:5]
	s_add_u32 m0, s100, 0xc000
	s_nop 0
	global_load_lds_dwordx4 v70, s[6:7]
	s_add_u32 m0, s100, 0x9000
	s_nop 0
	global_load_lds_dwordx4 v72, s[4:5]
	s_add_u32 m0, s100, 0xd000
	s_nop 0
	global_load_lds_dwordx4 v72, s[6:7]
	s_add_u32 m0, s100, 0xa000
	s_nop 0
	global_load_lds_dwordx4 v74, s[4:5]
	s_add_u32 m0, s100, 0xe000
	s_nop 0
	global_load_lds_dwordx4 v74, s[6:7]
	s_add_u32 m0, s100, 0xb000
	s_nop 0
	global_load_lds_dwordx4 v76, s[4:5]
	s_add_u32 m0, s100, 0xf000
	s_nop 0
	global_load_lds_dwordx4 v76, s[6:7]
	s_waitcnt vmcnt(8)
	s_barrier
	ds_read_b128 v[94:97], v226 offset:0
	ds_read_b128 v[98:101], v226 offset:2048
	ds_read_b128 v[102:105], v226 offset:4096
	ds_read_b128 v[106:109], v226 offset:6144
	ds_read_b128 v[110:113], v227 offset:16384
	ds_read_b128 v[114:117], v227 offset:18432
	ds_read_b128 v[118:121], v227 offset:20480
	ds_read_b128 v[122:125], v227 offset:22528
	ds_read_b128 v[126:129], v91 offset:0
	ds_read_b128 v[130:133], v91 offset:2048
	ds_read_b128 v[134:137], v91 offset:4096
	ds_read_b128 v[138:141], v91 offset:6144
	ds_read_b128 v[142:145], v92 offset:16384
	ds_read_b128 v[152:155], v92 offset:18432
	ds_read_b128 v[156:159], v92 offset:20480
	ds_read_b128 v[178:181], v92 offset:22528
	s_waitcnt lgkmcnt(0)
	s_barrier
	s_and_b32 s4, s34, 0x3c0
	s_lshl_b32 s6, s4, 1
	s_add_u32 s4, s39, s6
	s_addc_u32 s5, s45, 0
	s_add_u32 s6, s49, s6
	s_addc_u32 s7, s51, 0
	s_add_i32 s34, s34, 64
	s_add_u32 m0, s100, 0x0
	s_nop 0
	global_load_lds_dwordx4 v70, s[4:5]
	s_add_u32 m0, s100, 0x4000
	s_nop 0
	global_load_lds_dwordx4 v70, s[6:7]
	s_add_u32 m0, s100, 0x1000
	s_nop 0
	global_load_lds_dwordx4 v72, s[4:5]
	s_add_u32 m0, s100, 0x5000
	s_nop 0
	global_load_lds_dwordx4 v72, s[6:7]
	s_add_u32 m0, s100, 0x2000
	s_nop 0
	global_load_lds_dwordx4 v74, s[4:5]
	s_add_u32 m0, s100, 0x6000
	s_nop 0
	global_load_lds_dwordx4 v74, s[6:7]
	s_add_u32 m0, s100, 0x3000
	s_nop 0
	global_load_lds_dwordx4 v76, s[4:5]
	s_add_u32 m0, s100, 0x7000
	s_nop 0
	global_load_lds_dwordx4 v76, s[6:7]
	s_waitcnt vmcnt(8)
	s_branch .Lgp_k0
.Lgp_have:
	s_add_i32 s34, s34, 0xc0
	s_waitcnt vmcnt(40)

; DI float sigm(float x) { return __builtin_amdgcn_rcpf(1.f + __expf(-x)); }
; DI void phase_merge(const Params& p, int l, LAS char* lds) {
;     ...
;         if (gate) {
; #pragma unroll
;             for (int ni = 0; ni < 4; ++ni) {
;                 const f32x4 bv = bvv[ni];
; #pragma unroll
;                 for (int mi = 0; mi < 4; ++mi) {
;                     const f32x4 a = acc[mi][ni] + bv;
;                     const unsigned q0 = (unsigned)(fmaxf(sigm(a[0]) * 255.f, 1.f) + 0.5f), q1 = (unsigned)(fmaxf(sigm(a[1]) * 255.f, 1.f) + 0.5f);
;                     const unsigned q2 = (unsigned)(fmaxf(sigm(a[2]) * 255.f, 1.f) + 0.5f), q3 = (unsigned)(fmaxf(sigm(a[3]) * 255.f, 1.f) + 0.5f);
;                     st[(mi * 4 + ni) * 256] = q0 | (q1 << 8) | (q2 << 16) | (q3 << 24);
;                 }
;             }
.Lgpk15_dn:
	s_setprio 0
	s_lshl_b32 s5, s55, 2
	s_add_u32 s5, s5, s54
	s_lshl_b32 s5, s5, 14
	s_add_u32 s58, s60, s5
	s_addc_u32 s59, s61, 0
	v_add_f32_e32 v186, v66, v62
	v_add_f32_e32 v187, v68, v63
	v_add_f32_e32 v188, v69, v64
	v_add_f32_e32 v189, v93, v65
	v_mul_f32_e32 v186, 0xbfb8aa3b, v186
	v_mul_f32_e32 v187, 0xbfb8aa3b, v187
	v_mul_f32_e32 v188, 0xbfb8aa3b, v188
	v_mul_f32_e32 v189, 0xbfb8aa3b, v189
	v_exp_f32_e32 v186, v186
	v_exp_f32_e32 v187, v187
	v_exp_f32_e32 v188, v188
	v_exp_f32_e32 v189, v189
	v_add_f32_e32 v186, 1.0, v186
	v_add_f32_e32 v187, 1.0, v187
	v_add_f32_e32 v188, 1.0, v188
	v_add_f32_e32 v189, 1.0, v189
	v_rcp_f32_e32 v186, v186
	v_rcp_f32_e32 v187, v187
	v_rcp_f32_e32 v188, v188
	v_rcp_f32_e32 v189, v189
	v_mul_f32_e32 v186, 0x437f0000, v186
	v_mul_f32_e32 v187, 0x437f0000, v187
	v_mul_f32_e32 v188, 0x437f0000, v188
	v_mul_f32_e32 v189, 0x437f0000, v189
	v_max_f32_e32 v186, 1.0, v186
	v_max_f32_e32 v187, 1.0, v187
	v_max_f32_e32 v188, 1.0, v188
	v_max_f32_e32 v189, 1.0, v189
	v_add_f32_e32 v186, 0.5, v186
	v_add_f32_e32 v187, 0.5, v187
	v_add_f32_e32 v188, 0.5, v188
	v_add_f32_e32 v189, 0.5, v189
	v_cvt_u32_f32_e32 v186, v186
	v_cvt_u32_f32_e32 v187, v187
	v_cvt_u32_f32_sdwa v188, v188 dst_sel:WORD_1 dst_unused:UNUSED_PAD src0_sel:DWORD
	v_cvt_u32_f32_sdwa v189, v189 dst_sel:BYTE_3 dst_unused:UNUSED_PAD src0_sel:DWORD
	v_lshl_or_b32 v186, v187, 8, v186
	s_nop 0
	v_or3_b32 v186, v186, v188, v189
	global_store_dword v1, v186, s[58:59] offset:0
	v_add_f32_e32 v190, v146, v58
	v_add_f32_e32 v191, v147, v59
	v_add_f32_e32 v192, v148, v60
	v_add_f32_e32 v193, v160, v61
	v_mul_f32_e32 v190, 0xbfb8aa3b, v190
	v_mul_f32_e32 v191, 0xbfb8aa3b, v191
	v_mul_f32_e32 v192, 0xbfb8aa3b, v192
	v_mul_f32_e32 v193, 0xbfb8aa3b, v193
	v_exp_f32_e32 v190, v190
	v_exp_f32_e32 v191, v191
	v_exp_f32_e32 v192, v192
	v_exp_f32_e32 v193, v193
	v_add_f32_e32 v190, 1.0, v190
	v_add_f32_e32 v191, 1.0, v191
	v_add_f32_e32 v192, 1.0, v192
	v_add_f32_e32 v193, 1.0, v193
	v_rcp_f32_e32 v190, v190
	v_rcp_f32_e32 v191, v191
	v_rcp_f32_e32 v192, v192
	v_rcp_f32_e32 v193, v193
	v_mul_f32_e32 v190, 0x437f0000, v190
	v_mul_f32_e32 v191, 0x437f0000, v191
	v_mul_f32_e32 v192, 0x437f0000, v192
	v_mul_f32_e32 v193, 0x437f0000, v193
	v_max_f32_e32 v190, 1.0, v190
	v_max_f32_e32 v191, 1.0, v191
	v_max_f32_e32 v192, 1.0, v192
	v_max_f32_e32 v193, 1.0, v193
	v_add_f32_e32 v190, 0.5, v190
	v_add_f32_e32 v191, 0.5, v191
	v_add_f32_e32 v192, 0.5, v192
	v_add_f32_e32 v193, 0.5, v193
	v_cvt_u32_f32_e32 v190, v190
	v_cvt_u32_f32_e32 v191, v191
	v_cvt_u32_f32_sdwa v192, v192 dst_sel:WORD_1 dst_unused:UNUSED_PAD src0_sel:DWORD
	v_cvt_u32_f32_sdwa v193, v193 dst_sel:BYTE_3 dst_unused:UNUSED_PAD src0_sel:DWORD
	v_lshl_or_b32 v190, v191, 8, v190
	s_nop 0
	v_or3_b32 v190, v190, v192, v193
	global_store_dword v1, v190, s[58:59] offset:1024
	v_add_f32_e32 v186, v161, v54
	v_add_f32_e32 v187, v182, v55
	v_add_f32_e32 v188, v183, v56
	v_add_f32_e32 v189, v184, v57
	v_mul_f32_e32 v186, 0xbfb8aa3b, v186
	v_mul_f32_e32 v187, 0xbfb8aa3b, v187
	v_mul_f32_e32 v188, 0xbfb8aa3b, v188
	v_mul_f32_e32 v189, 0xbfb8aa3b, v189
	v_exp_f32_e32 v186, v186
	v_exp_f32_e32 v187, v187
	v_exp_f32_e32 v188, v188
	v_exp_f32_e32 v189, v189
	v_add_f32_e32 v186, 1.0, v186
	v_add_f32_e32 v187, 1.0, v187
	v_add_f32_e32 v188, 1.0, v188
	v_add_f32_e32 v189, 1.0, v189
	v_rcp_f32_e32 v186, v186
	v_rcp_f32_e32 v187, v187
	v_rcp_f32_e32 v188, v188
	v_rcp_f32_e32 v189, v189
	v_mul_f32_e32 v186, 0x437f0000, v186
	v_mul_f32_e32 v187, 0x437f0000, v187
	v_mul_f32_e32 v188, 0x437f0000, v188
	v_mul_f32_e32 v189, 0x437f0000, v189
	v_max_f32_e32 v186, 1.0, v186
	v_max_f32_e32 v187, 1.0, v187
	v_max_f32_e32 v188, 1.0, v188
	v_max_f32_e32 v189, 1.0, v189
	v_add_f32_e32 v186, 0.5, v186
	v_add_f32_e32 v187, 0.5, v187
	v_add_f32_e32 v188, 0.5, v188
	v_add_f32_e32 v189, 0.5, v189
	v_cvt_u32_f32_e32 v186, v186
	v_cvt_u32_f32_e32 v187, v187
	v_cvt_u32_f32_sdwa v188, v188 dst_sel:WORD_1 dst_unused:UNUSED_PAD src0_sel:DWORD
	v_cvt_u32_f32_sdwa v189, v189 dst_sel:BYTE_3 dst_unused:UNUSED_PAD src0_sel:DWORD
	v_lshl_or_b32 v186, v187, 8, v186
	s_nop 0
	v_or3_b32 v186, v186, v188, v189
	global_store_dword v1, v186, s[58:59] offset:2048
	v_add_f32_e32 v190, v185, v50
	v_add_f32_e32 v191, v71, v51
	v_add_f32_e32 v192, v73, v52
	v_add_f32_e32 v193, v75, v53
	v_mul_f32_e32 v190, 0xbfb8aa3b, v190
	v_mul_f32_e32 v191, 0xbfb8aa3b, v191
	v_mul_f32_e32 v192, 0xbfb8aa3b, v192
	v_mul_f32_e32 v193, 0xbfb8aa3b, v193
	v_exp_f32_e32 v190, v190
	v_exp_f32_e32 v191, v191
	v_exp_f32_e32 v192, v192
	v_exp_f32_e32 v193, v193
	v_add_f32_e32 v190, 1.0, v190
	v_add_f32_e32 v191, 1.0, v191
	v_add_f32_e32 v192, 1.0, v192
	v_add_f32_e32 v193, 1.0, v193
	v_rcp_f32_e32 v190, v190
	v_rcp_f32_e32 v191, v191
	v_rcp_f32_e32 v192, v192
	v_rcp_f32_e32 v193, v193
	v_mul_f32_e32 v190, 0x437f0000, v190
	v_mul_f32_e32 v191, 0x437f0000, v191
	v_mul_f32_e32 v192, 0x437f0000, v192
	v_mul_f32_e32 v193, 0x437f0000, v193
	v_max_f32_e32 v190, 1.0, v190
	v_max_f32_e32 v191, 1.0, v191
	v_max_f32_e32 v192, 1.0, v192
	v_max_f32_e32 v193, 1.0, v193
	v_add_f32_e32 v190, 0.5, v190
	v_add_f32_e32 v191, 0.5, v191
	v_add_f32_e32 v192, 0.5, v192
	v_add_f32_e32 v193, 0.5, v193
	v_cvt_u32_f32_e32 v190, v190
	v_cvt_u32_f32_e32 v191, v191
	v_cvt_u32_f32_sdwa v192, v192 dst_sel:WORD_1 dst_unused:UNUSED_PAD src0_sel:DWORD
	v_cvt_u32_f32_sdwa v193, v193 dst_sel:BYTE_3 dst_unused:UNUSED_PAD src0_sel:DWORD
	v_lshl_or_b32 v190, v191, 8, v190
	s_nop 0
	v_or3_b32 v190, v190, v192, v193
	global_store_dword v1, v190, s[58:59] offset:3072
	s_add_u32 s58, s58, 0x1000
	s_addc_u32 s59, s59, 0
; DI float sigm(float x) { return __builtin_amdgcn_rcpf(1.f + __expf(-x)); }
; DI void phase_merge(const Params& p, int l, LAS char* lds) {
;     ...
;         if (gate) {
; #pragma unroll
;             for (int ni = 0; ni < 4; ++ni) {
;                 const f32x4 bv = bvv[ni];
; #pragma unroll
;                 for (int mi = 0; mi < 4; ++mi) {
;                     const f32x4 a = acc[mi][ni] + bv;
;                     const unsigned q0 = (unsigned)(fmaxf(sigm(a[0]) * 255.f, 1.f) + 0.5f), q1 = (unsigned)(fmaxf(sigm(a[1]) * 255.f, 1.f) + 0.5f);
;                     const unsigned q2 = (unsigned)(fmaxf(sigm(a[2]) * 255.f, 1.f) + 0.5f), q3 = (unsigned)(fmaxf(sigm(a[3]) * 255.f, 1.f) + 0.5f);
;                     st[(mi * 4 + ni) * 256] = q0 | (q1 << 8) | (q2 << 16) | (q3 << 24);
;                 }
;             }
	v_add_f32_e32 v186, v66, v46
	v_add_f32_e32 v187, v68, v47
	v_add_f32_e32 v188, v69, v48
	v_add_f32_e32 v189, v93, v49
	v_mul_f32_e32 v186, 0xbfb8aa3b, v186
	v_mul_f32_e32 v187, 0xbfb8aa3b, v187
	v_mul_f32_e32 v188, 0xbfb8aa3b, v188
	v_mul_f32_e32 v189, 0xbfb8aa3b, v189
	v_exp_f32_e32 v186, v186
	v_exp_f32_e32 v187, v187
	v_exp_f32_e32 v188, v188
	v_exp_f32_e32 v189, v189
	v_add_f32_e32 v186, 1.0, v186
	v_add_f32_e32 v187, 1.0, v187
	v_add_f32_e32 v188, 1.0, v188
	v_add_f32_e32 v189, 1.0, v189
	v_rcp_f32_e32 v186, v186
	v_rcp_f32_e32 v187, v187
	v_rcp_f32_e32 v188, v188
	v_rcp_f32_e32 v189, v189
	v_mul_f32_e32 v186, 0x437f0000, v186
	v_mul_f32_e32 v187, 0x437f0000, v187
	v_mul_f32_e32 v188, 0x437f0000, v188
	v_mul_f32_e32 v189, 0x437f0000, v189
	v_max_f32_e32 v186, 1.0, v186
	v_max_f32_e32 v187, 1.0, v187
	v_max_f32_e32 v188, 1.0, v188
	v_max_f32_e32 v189, 1.0, v189
	v_add_f32_e32 v186, 0.5, v186
	v_add_f32_e32 v187, 0.5, v187
	v_add_f32_e32 v188, 0.5, v188
	v_add_f32_e32 v189, 0.5, v189
	v_cvt_u32_f32_e32 v186, v186
	v_cvt_u32_f32_e32 v187, v187
	v_cvt_u32_f32_sdwa v188, v188 dst_sel:WORD_1 dst_unused:UNUSED_PAD src0_sel:DWORD
	v_cvt_u32_f32_sdwa v189, v189 dst_sel:BYTE_3 dst_unused:UNUSED_PAD src0_sel:DWORD
	v_lshl_or_b32 v186, v187, 8, v186
	s_nop 0
	v_or3_b32 v186, v186, v188, v189
	global_store_dword v1, v186, s[58:59] offset:0
	v_add_f32_e32 v190, v146, v42
	v_add_f32_e32 v191, v147, v43
	v_add_f32_e32 v192, v148, v44
	v_add_f32_e32 v193, v160, v45
	v_mul_f32_e32 v190, 0xbfb8aa3b, v190
	v_mul_f32_e32 v191, 0xbfb8aa3b, v191
	v_mul_f32_e32 v192, 0xbfb8aa3b, v192
	v_mul_f32_e32 v193, 0xbfb8aa3b, v193
	v_exp_f32_e32 v190, v190
	v_exp_f32_e32 v191, v191
	v_exp_f32_e32 v192, v192
	v_exp_f32_e32 v193, v193
	v_add_f32_e32 v190, 1.0, v190
	v_add_f32_e32 v191, 1.0, v191
	v_add_f32_e32 v192, 1.0, v192
	v_add_f32_e32 v193, 1.0, v193
	v_rcp_f32_e32 v190, v190
	v_rcp_f32_e32 v191, v191
	v_rcp_f32_e32 v192, v192
	v_rcp_f32_e32 v193, v193
	v_mul_f32_e32 v190, 0x437f0000, v190
	v_mul_f32_e32 v191, 0x437f0000, v191
	v_mul_f32_e32 v192, 0x437f0000, v192
	v_mul_f32_e32 v193, 0x437f0000, v193
	v_max_f32_e32 v190, 1.0, v190
	v_max_f32_e32 v191, 1.0, v191
	v_max_f32_e32 v192, 1.0, v192
	v_max_f32_e32 v193, 1.0, v193
	v_add_f32_e32 v190, 0.5, v190
	v_add_f32_e32 v191, 0.5, v191
	v_add_f32_e32 v192, 0.5, v192
	v_add_f32_e32 v193, 0.5, v193
	v_cvt_u32_f32_e32 v190, v190
	v_cvt_u32_f32_e32 v191, v191
	v_cvt_u32_f32_sdwa v192, v192 dst_sel:WORD_1 dst_unused:UNUSED_PAD src0_sel:DWORD
	v_cvt_u32_f32_sdwa v193, v193 dst_sel:BYTE_3 dst_unused:UNUSED_PAD src0_sel:DWORD
	v_lshl_or_b32 v190, v191, 8, v190
	s_nop 0
	v_or3_b32 v190, v190, v192, v193
	global_store_dword v1, v190, s[58:59] offset:1024
	v_add_f32_e32 v186, v161, v38
	v_add_f32_e32 v187, v182, v39
	v_add_f32_e32 v188, v183, v40
	v_add_f32_e32 v189, v184, v41
	v_mul_f32_e32 v186, 0xbfb8aa3b, v186
	v_mul_f32_e32 v187, 0xbfb8aa3b, v187
	v_mul_f32_e32 v188, 0xbfb8aa3b, v188
	v_mul_f32_e32 v189, 0xbfb8aa3b, v189
	v_exp_f32_e32 v186, v186
	v_exp_f32_e32 v187, v187
	v_exp_f32_e32 v188, v188
	v_exp_f32_e32 v189, v189
	v_add_f32_e32 v186, 1.0, v186
	v_add_f32_e32 v187, 1.0, v187
	v_add_f32_e32 v188, 1.0, v188
	v_add_f32_e32 v189, 1.0, v189
	v_rcp_f32_e32 v186, v186
	v_rcp_f32_e32 v187, v187
	v_rcp_f32_e32 v188, v188
	v_rcp_f32_e32 v189, v189
	v_mul_f32_e32 v186, 0x437f0000, v186
	v_mul_f32_e32 v187, 0x437f0000, v187
	v_mul_f32_e32 v188, 0x437f0000, v188
	v_mul_f32_e32 v189, 0x437f0000, v189
	v_max_f32_e32 v186, 1.0, v186
	v_max_f32_e32 v187, 1.0, v187
	v_max_f32_e32 v188, 1.0, v188
	v_max_f32_e32 v189, 1.0, v189
	v_add_f32_e32 v186, 0.5, v186
	v_add_f32_e32 v187, 0.5, v187
	v_add_f32_e32 v188, 0.5, v188
	v_add_f32_e32 v189, 0.5, v189
	v_cvt_u32_f32_e32 v186, v186
	v_cvt_u32_f32_e32 v187, v187
	v_cvt_u32_f32_sdwa v188, v188 dst_sel:WORD_1 dst_unused:UNUSED_PAD src0_sel:DWORD
	v_cvt_u32_f32_sdwa v189, v189 dst_sel:BYTE_3 dst_unused:UNUSED_PAD src0_sel:DWORD
	v_lshl_or_b32 v186, v187, 8, v186
	s_nop 0
	v_or3_b32 v186, v186, v188, v189
	global_store_dword v1, v186, s[58:59] offset:2048
	v_add_f32_e32 v190, v185, v34
	v_add_f32_e32 v191, v71, v35
	v_add_f32_e32 v192, v73, v36
	v_add_f32_e32 v193, v75, v37
	v_mul_f32_e32 v190, 0xbfb8aa3b, v190
	v_mul_f32_e32 v191, 0xbfb8aa3b, v191
	v_mul_f32_e32 v192, 0xbfb8aa3b, v192
	v_mul_f32_e32 v193, 0xbfb8aa3b, v193
	v_exp_f32_e32 v190, v190
	v_exp_f32_e32 v191, v191
	v_exp_f32_e32 v192, v192
	v_exp_f32_e32 v193, v193
	v_add_f32_e32 v190, 1.0, v190
	v_add_f32_e32 v191, 1.0, v191
	v_add_f32_e32 v192, 1.0, v192
	v_add_f32_e32 v193, 1.0, v193
	v_rcp_f32_e32 v190, v190
	v_rcp_f32_e32 v191, v191
	v_rcp_f32_e32 v192, v192
	v_rcp_f32_e32 v193, v193
	v_mul_f32_e32 v190, 0x437f0000, v190
	v_mul_f32_e32 v191, 0x437f0000, v191
	v_mul_f32_e32 v192, 0x437f0000, v192
	v_mul_f32_e32 v193, 0x437f0000, v193
	v_max_f32_e32 v190, 1.0, v190
	v_max_f32_e32 v191, 1.0, v191
	v_max_f32_e32 v192, 1.0, v192
	v_max_f32_e32 v193, 1.0, v193
	v_add_f32_e32 v190, 0.5, v190
	v_add_f32_e32 v191, 0.5, v191
	v_add_f32_e32 v192, 0.5, v192
	v_add_f32_e32 v193, 0.5, v193
	v_cvt_u32_f32_e32 v190, v190
	v_cvt_u32_f32_e32 v191, v191
	v_cvt_u32_f32_sdwa v192, v192 dst_sel:WORD_1 dst_unused:UNUSED_PAD src0_sel:DWORD
	v_cvt_u32_f32_sdwa v193, v193 dst_sel:BYTE_3 dst_unused:UNUSED_PAD src0_sel:DWORD
	v_lshl_or_b32 v190, v191, 8, v190
	s_nop 0
	v_or3_b32 v190, v190, v192, v193
	global_store_dword v1, v190, s[58:59] offset:3072
	s_add_u32 s58, s58, 0x1000
	s_addc_u32 s59, s59, 0
	v_add_f32_e32 v186, v66, v30
	v_add_f32_e32 v187, v68, v31
	v_add_f32_e32 v188, v69, v32
	v_add_f32_e32 v189, v93, v33
	v_mul_f32_e32 v186, 0xbfb8aa3b, v186
; DI float sigm(float x) { return __builtin_amdgcn_rcpf(1.f + __expf(-x)); }
; DI void phase_merge(const Params& p, int l, LAS char* lds) {
;     ...
;         if (gate) {
; #pragma unroll
;             for (int ni = 0; ni < 4; ++ni) {
;                 const f32x4 bv = bvv[ni];
; #pragma unroll
;                 for (int mi = 0; mi < 4; ++mi) {
;                     const f32x4 a = acc[mi][ni] + bv;
;                     const unsigned q0 = (unsigned)(fmaxf(sigm(a[0]) * 255.f, 1.f) + 0.5f), q1 = (unsigned)(fmaxf(sigm(a[1]) * 255.f, 1.f) + 0.5f);
;                     const unsigned q2 = (unsigned)(fmaxf(sigm(a[2]) * 255.f, 1.f) + 0.5f), q3 = (unsigned)(fmaxf(sigm(a[3]) * 255.f, 1.f) + 0.5f);
;                     st[(mi * 4 + ni) * 256] = q0 | (q1 << 8) | (q2 << 16) | (q3 << 24);
;                 }
;             }
	v_mul_f32_e32 v187, 0xbfb8aa3b, v187
	v_mul_f32_e32 v188, 0xbfb8aa3b, v188
	v_mul_f32_e32 v189, 0xbfb8aa3b, v189
	v_exp_f32_e32 v186, v186
	v_exp_f32_e32 v187, v187
	v_exp_f32_e32 v188, v188
	v_exp_f32_e32 v189, v189
	v_add_f32_e32 v186, 1.0, v186
	v_add_f32_e32 v187, 1.0, v187
	v_add_f32_e32 v188, 1.0, v188
	v_add_f32_e32 v189, 1.0, v189
	v_rcp_f32_e32 v186, v186
	v_rcp_f32_e32 v187, v187
	v_rcp_f32_e32 v188, v188
	v_rcp_f32_e32 v189, v189
	v_mul_f32_e32 v186, 0x437f0000, v186
	v_mul_f32_e32 v187, 0x437f0000, v187
	v_mul_f32_e32 v188, 0x437f0000, v188
	v_mul_f32_e32 v189, 0x437f0000, v189
	v_max_f32_e32 v186, 1.0, v186
	v_max_f32_e32 v187, 1.0, v187
	v_max_f32_e32 v188, 1.0, v188
	v_max_f32_e32 v189, 1.0, v189
	v_add_f32_e32 v186, 0.5, v186
	v_add_f32_e32 v187, 0.5, v187
	v_add_f32_e32 v188, 0.5, v188
	v_add_f32_e32 v189, 0.5, v189
	v_cvt_u32_f32_e32 v186, v186
	v_cvt_u32_f32_e32 v187, v187
	v_cvt_u32_f32_sdwa v188, v188 dst_sel:WORD_1 dst_unused:UNUSED_PAD src0_sel:DWORD
	v_cvt_u32_f32_sdwa v189, v189 dst_sel:BYTE_3 dst_unused:UNUSED_PAD src0_sel:DWORD
	v_lshl_or_b32 v186, v187, 8, v186
	s_nop 0
	v_or3_b32 v186, v186, v188, v189
	global_store_dword v1, v186, s[58:59] offset:0
	v_add_f32_e32 v190, v146, v26
	v_add_f32_e32 v191, v147, v27
	v_add_f32_e32 v192, v148, v28
	v_add_f32_e32 v193, v160, v29
	v_mul_f32_e32 v190, 0xbfb8aa3b, v190
	v_mul_f32_e32 v191, 0xbfb8aa3b, v191
	v_mul_f32_e32 v192, 0xbfb8aa3b, v192
	v_mul_f32_e32 v193, 0xbfb8aa3b, v193
	v_exp_f32_e32 v190, v190
	v_exp_f32_e32 v191, v191
	v_exp_f32_e32 v192, v192
	v_exp_f32_e32 v193, v193
	v_add_f32_e32 v190, 1.0, v190
	v_add_f32_e32 v191, 1.0, v191
	v_add_f32_e32 v192, 1.0, v192
	v_add_f32_e32 v193, 1.0, v193
	v_rcp_f32_e32 v190, v190
	v_rcp_f32_e32 v191, v191
	v_rcp_f32_e32 v192, v192
	v_rcp_f32_e32 v193, v193
	v_mul_f32_e32 v190, 0x437f0000, v190
	v_mul_f32_e32 v191, 0x437f0000, v191
	v_mul_f32_e32 v192, 0x437f0000, v192
	v_mul_f32_e32 v193, 0x437f0000, v193
	v_max_f32_e32 v190, 1.0, v190
	v_max_f32_e32 v191, 1.0, v191
	v_max_f32_e32 v192, 1.0, v192
	v_max_f32_e32 v193, 1.0, v193
	v_add_f32_e32 v190, 0.5, v190
	v_add_f32_e32 v191, 0.5, v191
	v_add_f32_e32 v192, 0.5, v192
	v_add_f32_e32 v193, 0.5, v193
	v_cvt_u32_f32_e32 v190, v190
	v_cvt_u32_f32_e32 v191, v191
	v_cvt_u32_f32_sdwa v192, v192 dst_sel:WORD_1 dst_unused:UNUSED_PAD src0_sel:DWORD
	v_cvt_u32_f32_sdwa v193, v193 dst_sel:BYTE_3 dst_unused:UNUSED_PAD src0_sel:DWORD
	v_lshl_or_b32 v190, v191, 8, v190
	s_nop 0
	v_or3_b32 v190, v190, v192, v193
	global_store_dword v1, v190, s[58:59] offset:1024
	v_add_f32_e32 v186, v161, v22
	v_add_f32_e32 v187, v182, v23
	v_add_f32_e32 v188, v183, v24
	v_add_f32_e32 v189, v184, v25
	v_mul_f32_e32 v186, 0xbfb8aa3b, v186
	v_mul_f32_e32 v187, 0xbfb8aa3b, v187
	v_mul_f32_e32 v188, 0xbfb8aa3b, v188
	v_mul_f32_e32 v189, 0xbfb8aa3b, v189
	v_exp_f32_e32 v186, v186
	v_exp_f32_e32 v187, v187
	v_exp_f32_e32 v188, v188
	v_exp_f32_e32 v189, v189
	v_add_f32_e32 v186, 1.0, v186
	v_add_f32_e32 v187, 1.0, v187
	v_add_f32_e32 v188, 1.0, v188
	v_add_f32_e32 v189, 1.0, v189
	v_rcp_f32_e32 v186, v186
	v_rcp_f32_e32 v187, v187
	v_rcp_f32_e32 v188, v188
	v_rcp_f32_e32 v189, v189
	v_mul_f32_e32 v186, 0x437f0000, v186
	v_mul_f32_e32 v187, 0x437f0000, v187
	v_mul_f32_e32 v188, 0x437f0000, v188
	v_mul_f32_e32 v189, 0x437f0000, v189
	v_max_f32_e32 v186, 1.0, v186
	v_max_f32_e32 v187, 1.0, v187
	v_max_f32_e32 v188, 1.0, v188
	v_max_f32_e32 v189, 1.0, v189
	v_add_f32_e32 v186, 0.5, v186
	v_add_f32_e32 v187, 0.5, v187
	v_add_f32_e32 v188, 0.5, v188
	v_add_f32_e32 v189, 0.5, v189
	v_cvt_u32_f32_e32 v186, v186
	v_cvt_u32_f32_e32 v187, v187
	v_cvt_u32_f32_sdwa v188, v188 dst_sel:WORD_1 dst_unused:UNUSED_PAD src0_sel:DWORD
	v_cvt_u32_f32_sdwa v189, v189 dst_sel:BYTE_3 dst_unused:UNUSED_PAD src0_sel:DWORD
	v_lshl_or_b32 v186, v187, 8, v186
	s_nop 0
	v_or3_b32 v186, v186, v188, v189
	global_store_dword v1, v186, s[58:59] offset:2048
	v_add_f32_e32 v190, v185, v18
	v_add_f32_e32 v191, v71, v19
	v_add_f32_e32 v192, v73, v20
	v_add_f32_e32 v193, v75, v21
	v_mul_f32_e32 v190, 0xbfb8aa3b, v190
	v_mul_f32_e32 v191, 0xbfb8aa3b, v191
	v_mul_f32_e32 v192, 0xbfb8aa3b, v192
	v_mul_f32_e32 v193, 0xbfb8aa3b, v193
	v_exp_f32_e32 v190, v190
	v_exp_f32_e32 v191, v191
	v_exp_f32_e32 v192, v192
	v_exp_f32_e32 v193, v193
	v_add_f32_e32 v190, 1.0, v190
	v_add_f32_e32 v191, 1.0, v191
	v_add_f32_e32 v192, 1.0, v192
	v_add_f32_e32 v193, 1.0, v193
	v_rcp_f32_e32 v190, v190
	v_rcp_f32_e32 v191, v191
	v_rcp_f32_e32 v192, v192
	v_rcp_f32_e32 v193, v193
	v_mul_f32_e32 v190, 0x437f0000, v190
	v_mul_f32_e32 v191, 0x437f0000, v191
	v_mul_f32_e32 v192, 0x437f0000, v192
	v_mul_f32_e32 v193, 0x437f0000, v193
	v_max_f32_e32 v190, 1.0, v190
	v_max_f32_e32 v191, 1.0, v191
	v_max_f32_e32 v192, 1.0, v192
	v_max_f32_e32 v193, 1.0, v193
	v_add_f32_e32 v190, 0.5, v190
	v_add_f32_e32 v191, 0.5, v191
	v_add_f32_e32 v192, 0.5, v192
	v_add_f32_e32 v193, 0.5, v193
	v_cvt_u32_f32_e32 v190, v190
	v_cvt_u32_f32_e32 v191, v191
	v_cvt_u32_f32_sdwa v192, v192 dst_sel:WORD_1 dst_unused:UNUSED_PAD src0_sel:DWORD
	v_cvt_u32_f32_sdwa v193, v193 dst_sel:BYTE_3 dst_unused:UNUSED_PAD src0_sel:DWORD
	v_lshl_or_b32 v190, v191, 8, v190
	s_nop 0
	v_or3_b32 v190, v190, v192, v193
	global_store_dword v1, v190, s[58:59] offset:3072
	s_add_u32 s58, s58, 0x1000
	s_addc_u32 s59, s59, 0
	v_add_f32_e32 v186, v66, v14
	v_add_f32_e32 v187, v68, v15
	v_add_f32_e32 v188, v69, v16
	v_add_f32_e32 v189, v93, v17
	v_mul_f32_e32 v186, 0xbfb8aa3b, v186
; DI float sigm(float x) { return __builtin_amdgcn_rcpf(1.f + __expf(-x)); }
; DI void phase_merge(const Params& p, int l, LAS char* lds) {
;     ...
;     for (int f = 0; f < nops; ++f) {
;         const bool gate = f < 4 * ntl;
;         int br, i;
;         if (gate) { br = f / ntl; i = vb + (f - br * ntl) * G; } else { const int f2 = f - 4 * ntl; br = f2 & 3; i = vb + (f2 >> 2) * G; }
;         const int mt = i >> 3, nt = i & 7;
;         const bool has_next = f + 1 < nops;
;         const GOp g = op_of(f), gn = op_of(has_next ? f + 1 : f);
;         unsigned* st = stash + (size_t)(i * 4 + br) * 4096;
;     ...
;         if (gate) {
; #pragma unroll
;             for (int ni = 0; ni < 4; ++ni) {
;                 const f32x4 bv = bvv[ni];
; #pragma unroll
;                 for (int mi = 0; mi < 4; ++mi) {
;                     const f32x4 a = acc[mi][ni] + bv;
;                     const unsigned q0 = (unsigned)(fmaxf(sigm(a[0]) * 255.f, 1.f) + 0.5f), q1 = (unsigned)(fmaxf(sigm(a[1]) * 255.f, 1.f) + 0.5f);
;                     const unsigned q2 = (unsigned)(fmaxf(sigm(a[2]) * 255.f, 1.f) + 0.5f), q3 = (unsigned)(fmaxf(sigm(a[3]) * 255.f, 1.f) + 0.5f);
;                     st[(mi * 4 + ni) * 256] = q0 | (q1 << 8) | (q2 << 16) | (q3 << 24);
;                 }
;             }
	v_mul_f32_e32 v187, 0xbfb8aa3b, v187
	v_mul_f32_e32 v188, 0xbfb8aa3b, v188
	v_mul_f32_e32 v189, 0xbfb8aa3b, v189
	v_exp_f32_e32 v186, v186
	v_exp_f32_e32 v187, v187
	v_exp_f32_e32 v188, v188
	v_exp_f32_e32 v189, v189
	v_add_f32_e32 v186, 1.0, v186
	v_add_f32_e32 v187, 1.0, v187
	v_add_f32_e32 v188, 1.0, v188
	v_add_f32_e32 v189, 1.0, v189
	v_rcp_f32_e32 v186, v186
	v_rcp_f32_e32 v187, v187
	v_rcp_f32_e32 v188, v188
	v_rcp_f32_e32 v189, v189
	v_mul_f32_e32 v186, 0x437f0000, v186
	v_mul_f32_e32 v187, 0x437f0000, v187
	v_mul_f32_e32 v188, 0x437f0000, v188
	v_mul_f32_e32 v189, 0x437f0000, v189
	v_max_f32_e32 v186, 1.0, v186
	v_max_f32_e32 v187, 1.0, v187
	v_max_f32_e32 v188, 1.0, v188
	v_max_f32_e32 v189, 1.0, v189
	v_add_f32_e32 v186, 0.5, v186
	v_add_f32_e32 v187, 0.5, v187
	v_add_f32_e32 v188, 0.5, v188
	v_add_f32_e32 v189, 0.5, v189
	v_cvt_u32_f32_e32 v186, v186
	v_cvt_u32_f32_e32 v187, v187
	v_cvt_u32_f32_sdwa v188, v188 dst_sel:WORD_1 dst_unused:UNUSED_PAD src0_sel:DWORD
	v_cvt_u32_f32_sdwa v189, v189 dst_sel:BYTE_3 dst_unused:UNUSED_PAD src0_sel:DWORD
	v_lshl_or_b32 v186, v187, 8, v186
	s_nop 0
	v_or3_b32 v186, v186, v188, v189
	global_store_dword v1, v186, s[58:59] offset:0
	v_add_f32_e32 v190, v146, v10
	v_add_f32_e32 v191, v147, v11
	v_add_f32_e32 v192, v148, v12
	v_add_f32_e32 v193, v160, v13
	v_mul_f32_e32 v190, 0xbfb8aa3b, v190
	v_mul_f32_e32 v191, 0xbfb8aa3b, v191
	v_mul_f32_e32 v192, 0xbfb8aa3b, v192
	v_mul_f32_e32 v193, 0xbfb8aa3b, v193
	v_exp_f32_e32 v190, v190
	v_exp_f32_e32 v191, v191
	v_exp_f32_e32 v192, v192
	v_exp_f32_e32 v193, v193
	v_add_f32_e32 v190, 1.0, v190
	v_add_f32_e32 v191, 1.0, v191
	v_add_f32_e32 v192, 1.0, v192
	v_add_f32_e32 v193, 1.0, v193
	v_rcp_f32_e32 v190, v190
	v_rcp_f32_e32 v191, v191
	v_rcp_f32_e32 v192, v192
	v_rcp_f32_e32 v193, v193
	v_mul_f32_e32 v190, 0x437f0000, v190
	v_mul_f32_e32 v191, 0x437f0000, v191
	v_mul_f32_e32 v192, 0x437f0000, v192
	v_mul_f32_e32 v193, 0x437f0000, v193
	v_max_f32_e32 v190, 1.0, v190
	v_max_f32_e32 v191, 1.0, v191
	v_max_f32_e32 v192, 1.0, v192
	v_max_f32_e32 v193, 1.0, v193
	v_add_f32_e32 v190, 0.5, v190
	v_add_f32_e32 v191, 0.5, v191
	v_add_f32_e32 v192, 0.5, v192
	v_add_f32_e32 v193, 0.5, v193
	v_cvt_u32_f32_e32 v190, v190
	v_cvt_u32_f32_e32 v191, v191
	v_cvt_u32_f32_sdwa v192, v192 dst_sel:WORD_1 dst_unused:UNUSED_PAD src0_sel:DWORD
	v_cvt_u32_f32_sdwa v193, v193 dst_sel:BYTE_3 dst_unused:UNUSED_PAD src0_sel:DWORD
	v_lshl_or_b32 v190, v191, 8, v190
	s_nop 0
	v_or3_b32 v190, v190, v192, v193
	global_store_dword v1, v190, s[58:59] offset:1024
	v_add_f32_e32 v186, v161, v6
	v_add_f32_e32 v187, v182, v7
	v_add_f32_e32 v188, v183, v8
	v_add_f32_e32 v189, v184, v9
	v_mul_f32_e32 v186, 0xbfb8aa3b, v186
	v_mul_f32_e32 v187, 0xbfb8aa3b, v187
	v_mul_f32_e32 v188, 0xbfb8aa3b, v188
	v_mul_f32_e32 v189, 0xbfb8aa3b, v189
	v_exp_f32_e32 v186, v186
	v_exp_f32_e32 v187, v187
	v_exp_f32_e32 v188, v188
	v_exp_f32_e32 v189, v189
	v_add_f32_e32 v186, 1.0, v186
	v_add_f32_e32 v187, 1.0, v187
	v_add_f32_e32 v188, 1.0, v188
	v_add_f32_e32 v189, 1.0, v189
	v_rcp_f32_e32 v186, v186
	v_rcp_f32_e32 v187, v187
	v_rcp_f32_e32 v188, v188
	v_rcp_f32_e32 v189, v189
	v_mul_f32_e32 v186, 0x437f0000, v186
	v_mul_f32_e32 v187, 0x437f0000, v187
	v_mul_f32_e32 v188, 0x437f0000, v188
	v_mul_f32_e32 v189, 0x437f0000, v189
	v_max_f32_e32 v186, 1.0, v186
	v_max_f32_e32 v187, 1.0, v187
	v_max_f32_e32 v188, 1.0, v188
	v_max_f32_e32 v189, 1.0, v189
	v_add_f32_e32 v186, 0.5, v186
	v_add_f32_e32 v187, 0.5, v187
	v_add_f32_e32 v188, 0.5, v188
	v_add_f32_e32 v189, 0.5, v189
	v_cvt_u32_f32_e32 v186, v186
	v_cvt_u32_f32_e32 v187, v187
	v_cvt_u32_f32_sdwa v188, v188 dst_sel:WORD_1 dst_unused:UNUSED_PAD src0_sel:DWORD
	v_cvt_u32_f32_sdwa v189, v189 dst_sel:BYTE_3 dst_unused:UNUSED_PAD src0_sel:DWORD
	v_lshl_or_b32 v186, v187, 8, v186
	s_nop 0
	v_or3_b32 v186, v186, v188, v189
	global_store_dword v1, v186, s[58:59] offset:2048
	v_add_f32_e32 v190, v185, v2
	v_add_f32_e32 v191, v71, v3
	v_add_f32_e32 v192, v73, v4
	v_add_f32_e32 v193, v75, v5
	v_mul_f32_e32 v190, 0xbfb8aa3b, v190
	v_mul_f32_e32 v191, 0xbfb8aa3b, v191
	v_mul_f32_e32 v192, 0xbfb8aa3b, v192
	v_mul_f32_e32 v193, 0xbfb8aa3b, v193
	v_exp_f32_e32 v190, v190
	v_exp_f32_e32 v191, v191
	v_exp_f32_e32 v192, v192
	v_exp_f32_e32 v193, v193
	v_add_f32_e32 v190, 1.0, v190
	v_add_f32_e32 v191, 1.0, v191
	v_add_f32_e32 v192, 1.0, v192
	v_add_f32_e32 v193, 1.0, v193
	v_rcp_f32_e32 v190, v190
	v_rcp_f32_e32 v191, v191
	v_rcp_f32_e32 v192, v192
	v_rcp_f32_e32 v193, v193
	v_mul_f32_e32 v190, 0x437f0000, v190
	v_mul_f32_e32 v191, 0x437f0000, v191
	v_mul_f32_e32 v192, 0x437f0000, v192
	v_mul_f32_e32 v193, 0x437f0000, v193
	v_max_f32_e32 v190, 1.0, v190
	v_max_f32_e32 v191, 1.0, v191
	v_max_f32_e32 v192, 1.0, v192
	v_max_f32_e32 v193, 1.0, v193
	v_add_f32_e32 v190, 0.5, v190
	v_add_f32_e32 v191, 0.5, v191
	v_add_f32_e32 v192, 0.5, v192
	v_add_f32_e32 v193, 0.5, v193
	v_cvt_u32_f32_e32 v190, v190
	v_cvt_u32_f32_e32 v191, v191
	v_cvt_u32_f32_sdwa v192, v192 dst_sel:WORD_1 dst_unused:UNUSED_PAD src0_sel:DWORD
	v_cvt_u32_f32_sdwa v193, v193 dst_sel:BYTE_3 dst_unused:UNUSED_PAD src0_sel:DWORD
	v_lshl_or_b32 v190, v191, 8, v190
	s_nop 0
	v_or3_b32 v190, v190, v192, v193
	global_store_dword v1, v190, s[58:59] offset:3072
	s_mov_b64 s[46:47], -1
	s_mov_b32 s56, s23
	s_and_b64 vcc, exec, s[42:43]
	s_cbranch_vccnz .Lgp_tile
.Lgp_done:
	s_mov_b64 s[46:47], 0
	s_mov_b32 s56, 0x7f807f81
	s_movk_i32 s57, 0xeff0
	s_mov_b32 s101, 1
	s_branch .LBB0_278

; DI void phase_merge(const Params& p, int l, LAS char* lds) {
;     ...
;     const int G = gridDim.x, NT = 257 * 8, vb = vblock();
;     const int ntl = (vb < NT) ? (NT - vb + G - 1) / G : 0;
;     const int nops = 8 * ntl;
;     auto op_of = [&](int f) {
;         if (f < 4 * ntl) {
;             const int br = f / ntl, i = vb + (f - br * ntl) * G, mt = i >> 3, nt = i & 7;
;             return GOp{h + (size_t)mt * 128 * 1024, W + W_IN + (size_t)(3328 + br * 1024 + nt * 128) * 1024, 1024, 1024, 1024, 2 * (mt + nt)};
;         }
;         const int f2 = f - 4 * ntl, k = f2 >> 2, br = f2 & 3, i = vb + k * G, mt = i >> 3, nt = i & 7;
;         const int koff = (br == 0) ? 0 : (br == 1) ? 256 : (br == 2) ? 768 : 1024;
;         const int kk = (br == 1) ? 512 : 256;
;         const size_t woff = (br == 0) ? W_OP : (br == 1) ? W_OM : (br == 2) ? W_OC : W_OS;
;         return GOp{u + (size_t)mt * 128 * 1280 + koff, W + woff + (size_t)nt * 128 * kk, 1280, kk, kk, mt + nt};
;     };
;     f32x4 acc[4][4];
;     bool inflight = false;
;     unsigned sq[4][4], sqn[4][4];
; #pragma unroll
;     for (int mi = 0; mi < 4; ++mi)
; #pragma unroll
;         for (int ni = 0; ni < 4; ++ni) { sq[mi][ni] = 0x01010101u; sqn[mi][ni] = 0x01010101u; }
;     for (int f = 0; f < nops; ++f) {
;         const bool gate = f < 4 * ntl;
;         int br, i;
;         if (gate) { br = f / ntl; i = vb + (f - br * ntl) * G; } else { const int f2 = f - 4 * ntl; br = f2 & 3; i = vb + (f2 >> 2) * G; }
;         const int mt = i >> 3, nt = i & 7;
;         const bool has_next = f + 1 < nops;
;         const GOp g = op_of(f), gn = op_of(has_next ? f + 1 : f);
;         unsigned* st = stash + (size_t)(i * 4 + br) * 4096;
;         if (gate || br == 0) zero_acc(acc);
;         if (!gate) {
; #pragma unroll
;             for (int mi = 0; mi < 4; ++mi)
; #pragma unroll
;                 for (int ni = 0; ni < 4; ++ni) sq[mi][ni] = sqn[mi][ni];
;             if (br > 0) {
; #pragma unroll
;                 for (int mi = 0; mi < 4; ++mi)
; #pragma unroll
;                     for (int ni = 0; ni < 4; ++ni) {
;                         const unsigned q = sq[mi][ni];
;                         acc[mi][ni][0] *= 255.f * __builtin_amdgcn_rcpf((float)(q & 0xffu)); acc[mi][ni][1] *= 255.f * __builtin_amdgcn_rcpf((float)((q >> 8) & 0xffu));
.LBB0_232:
	s_cmp_lt_i32 s60, 1
	s_cbranch_scc1 .LBB0_278
	v_readlane_b32 s4, v228, 30
	s_lshl_b32 s61, s60, 3
	s_mul_i32 s1, s4, 0x13a0000
	s_mul_hi_i32 s0, s4, 0x13a0000
	s_add_u32 s62, s98, s1
	s_addc_u32 s63, s99, s0
	s_lshl_b32 s0, s4, 12
	s_ashr_i32 s1, s0, 31
	v_readlane_b32 s4, v229, 45
	v_lshrrev_b32_e32 v5, 4, v2
	s_lshl_b64 s[0:1], s[0:1], 2
	v_readlane_b32 s12, v229, 53
	v_xor_b32_e32 v5, v5, v2
	v_readlane_b32 s13, v229, 54
	s_add_u32 s64, s12, s0
	v_lshlrev_b32_e32 v7, 4, v2
	v_lshlrev_b32_e32 v5, 3, v5
	s_addc_u32 s65, s13, s1
	v_readlane_b32 s12, v228, 19
	v_and_b32_e32 v178, 56, v5
	v_add_u32_e32 v5, 0x1000, v7
	v_readlane_b32 s13, v228, 20
	v_ashrrev_i32_e32 v3, 31, v2
	v_ashrrev_i32_e32 v179, 7, v5
	v_add_u32_e32 v5, 0x2000, v7
	v_lshl_add_u64 v[152:153], v[2:3], 2, s[12:13]
	v_lshrrev_b32_e32 v3, 2, v2
	v_ashrrev_i32_e32 v180, 7, v5
	v_add_u32_e32 v5, 0x3000, v7
	v_and_b32_e32 v6, 12, v3
	v_and_b32_e32 v3, 48, v2
	v_ashrrev_i32_e32 v181, 7, v5
	v_lshlrev_b32_e32 v5, 3, v2
	s_movk_i32 s0, 0x70
	v_and_b32_e32 v1, 15, v2
	v_bitop3_b32 v182, v5, s0, v3 bitop3:0x48
	v_ashrrev_i32_e32 v3, 1, v2
	s_movk_i32 s0, 0xffc0
	v_and_or_b32 v183, v3, s0, v1
	v_lshlrev_b32_e32 v1, 7, v2
	v_and_b32_e32 v185, 0x2780, v1
	v_cvt_f32_u32_e32 v1, s60
	v_readlane_b32 s18, v229, 59
	v_readlane_b32 s19, v229, 60
	v_readlane_b32 s18, v228, 17
	v_rcp_iflag_f32_e32 v1, v1
	v_and_b32_e32 v4, 64, v2
	v_readlane_b32 s19, v228, 18
	v_lshlrev_b32_e32 v148, 1, v4
	v_mul_f32_e32 v1, 0x4f7ffffe, v1
	v_cvt_u32_f32_e32 v1, v1
	v_and_b32_e32 v3, 16, v2
	s_sub_i32 s0, 0, s60
	v_readlane_b32 s14, v229, 55
	v_readfirstlane_b32 s1, v1
	v_readlane_b32 s15, v229, 56
	v_readlane_b32 s16, v229, 57
	v_readlane_b32 s17, v229, 58
	v_and_b32_e32 v160, 0xfffffc00, v7
	v_bfe_i32 v161, v2, 3, 25
	v_bitop3_b32 v7, v5, v2, 48 bitop3:0x78
	v_lshl_add_u64 v[8:9], s[18:19], 0, v[148:149]
	v_lshlrev_b32_e32 v148, 1, v3
	v_lshrrev_b32_e32 v2, 1, v2
	s_mul_i32 s0, s0, s1
	v_readlane_b32 s10, v229, 51
	v_readlane_b32 s16, v229, 63
	v_readlane_b32 s14, v229, 61
	v_lshl_add_u64 v[8:9], v[8:9], 0, v[148:149]
	v_and_b32_e32 v148, 16, v2
	s_mul_hi_u32 s0, s1, s0
	s_mov_b32 s10, 0x800000
	v_readlane_b32 s17, v228, 0
	v_readlane_b32 s15, v229, 62
	s_lshl_b32 s66, s60, 2
	v_lshlrev_b32_e32 v184, 7, v183
	v_bitop3_b32 v186, v7, 64, v168 bitop3:0x6c
	v_lshl_add_u64 v[154:155], v[8:9], 0, v[148:149]
	s_max_i32 s67, s61, 1
	s_mov_b32 s33, s66
	s_add_i32 s68, s1, s0
	s_mov_b64 s[40:41], 0
	v_mov_b32_e32 v203, 0x1010101
	v_lshlrev_b32_e32 v156, 2, v4
	v_lshlrev_b32_e32 v158, 2, v6
	v_mov_b32_e32 v204, 0x1010101
	v_mov_b32_e32 v205, 0x1010101
	v_mov_b32_e32 v206, 0x1010101
	v_mov_b32_e32 v207, 0x1010101
	v_mov_b32_e32 v208, 0x1010101
	v_mov_b32_e32 v209, 0x1010101
	v_mov_b32_e32 v210, 0x1010101
	v_mov_b32_e32 v211, 0x1010101
	v_mov_b32_e32 v212, 0x1010101
	v_mov_b32_e32 v213, 0x1010101
	v_mov_b32_e32 v214, 0x1010101
	v_mov_b32_e32 v215, 0x1010101
	v_mov_b32_e32 v216, 0x1010101
	v_mov_b32_e32 v217, 0x1010101
	v_mov_b32_e32 v218, 0x1010101
	v_mov_b32_e32 v199, 0x1010101
	v_mov_b32_e32 v200, 0x1010101
	v_mov_b32_e32 v201, 0x1010101
	v_mov_b32_e32 v202, 0x1010101
	v_mov_b32_e32 v195, 0x1010101
	v_mov_b32_e32 v196, 0x1010101
	v_mov_b32_e32 v197, 0x1010101
	v_mov_b32_e32 v198, 0x1010101
	v_mov_b32_e32 v191, 0x1010101
	v_mov_b32_e32 v192, 0x1010101
	v_mov_b32_e32 v193, 0x1010101
	v_mov_b32_e32 v194, 0x1010101
	v_mov_b32_e32 v187, 0x1010101
	v_mov_b32_e32 v188, 0x1010101
	v_mov_b32_e32 v189, 0x1010101
	v_mov_b32_e32 v190, 0x1010101
	v_readlane_b32 s5, v229, 46
	v_readlane_b32 s6, v229, 47
	v_readlane_b32 s7, v229, 48
	v_readlane_b32 s8, v229, 49
	v_readlane_b32 s9, v229, 50
	v_readlane_b32 s11, v229, 52
	s_lshl_b32 s52, s73, 2
	s_ashr_i32 s53, s52, 31
	s_lshl_b64 s[52:53], s[52:53], 14
	v_lshl_add_u64 v[84:85], v[152:153], 0, s[52:53]
	global_load_dword v190, v[84:85], off
	global_load_dword v189, v[84:85], off offset:1024
	global_load_dword v188, v[84:85], off offset:2048
	global_load_dword v187, v[84:85], off offset:3072
	s_mov_b64 s[54:55], 0x1000
	v_lshl_add_u64 v[86:87], v[84:85], 0, s[54:55]
	global_load_dword v194, v[86:87], off
	global_load_dword v193, v[86:87], off offset:1024
	global_load_dword v192, v[86:87], off offset:2048
	global_load_dword v191, v[86:87], off offset:3072
	s_mov_b64 s[54:55], 0x2000
	v_lshl_add_u64 v[86:87], v[84:85], 0, s[54:55]
	global_load_dword v198, v[86:87], off
	global_load_dword v197, v[86:87], off offset:1024
	global_load_dword v196, v[86:87], off offset:2048
	global_load_dword v195, v[86:87], off offset:3072
	s_mov_b64 s[54:55], 0x3000
	v_lshl_add_u64 v[86:87], v[84:85], 0, s[54:55]
	global_load_dword v202, v[86:87], off
	global_load_dword v201, v[86:87], off offset:1024
	global_load_dword v200, v[86:87], off offset:2048
	global_load_dword v199, v[86:87], off offset:3072
	s_waitcnt vmcnt(0)
	s_branch .LBB0_235
